# every phase-1 store write-through (rotary tables, beta/g, gate, out-projection weight quarters); barrier 2 no longer needs the L2 writeback
# speedup vs baseline: 1.0120x; 1.0120x over previous
.Lrope_loop:
	v_and_b32_e32 v232, 0xfffffe03, v250
	v_bfe_u32 v233, v250, 5, 4
	v_lshl_or_b32 v232, v233, 2, v232
	v_bfe_u32 v233, v250, 3, 2
	v_lshl_or_b32 v232, v233, 6, v232
	v_bfe_u32 v233, v250, 2, 1
	v_lshl_or_b32 v232, v233, 8, v232
	v_lshlrev_b32_e32 v232, 2, v232
	v_ashrrev_i32_e32 v244, 5, v250
	v_ashrrev_i32_e32 v245, 31, v244
	v_lshl_add_u64 v[244:245], v[244:245], 2, s[48:49]
	global_load_dword v243, v[244:245], off
	v_add_co_u32_e32 v244, vcc, 0x200000, v240
	v_add_u32_e32 v250, s6, v250
	s_nop 0
	v_addc_co_u32_e32 v245, vcc, 0, v241, vcc
	v_cmp_lt_i32_e32 vcc, s30, v250
	s_or_b64 s[24:25], vcc, s[24:25]
	s_waitcnt vmcnt(0)
	v_cvt_f32_i32_e32 v243, v243
	v_mul_f32_e32 v243, v242, v243
	v_cvt_f64_f32_e32 v[246:247], v243
	v_mul_f64 v[248:249], v[246:247], s[28:29]
	v_rndne_f64_e32 v[248:249], v[248:249]
	v_fma_f64 v[246:247], v[246:247], s[28:29], -v[248:249]
	v_cvt_f32_f64_e32 v243, v[246:247]
	v_cos_f32_e32 v246, v243
	v_sin_f32_e32 v243, v243
	global_store_dword v232, v246, s[98:99] sc1
	global_store_dword v232, v243, s[100:101] sc1
	v_lshl_add_u64 v[240:241], v[240:241], 0, s[22:23]
	s_andn2_b64 exec, exec, s[24:25]
	s_cbranch_execnz .Lrope_loop

.LBB0_115:
	s_waitcnt vmcnt(4)
	ds_write_b32 v110, v100
	ds_write_b32 v110, v101 offset:264
	ds_write_b32 v110, v102 offset:528
	ds_write_b32 v110, v103 offset:792
	ds_write_b32 v110, v104 offset:1056
	ds_write_b32 v110, v105 offset:1320
	ds_write_b32 v110, v106 offset:1584
	ds_write_b32 v110, v107 offset:1848
	s_waitcnt lgkmcnt(0)
	ds_read_b32 v112, v111
	ds_read_b32 v113, v111 offset:132
	ds_read_b32 v114, v111 offset:264
	ds_read_b32 v115, v111 offset:396
	ds_read_b32 v116, v111 offset:528
	ds_read_b32 v117, v111 offset:660
	ds_read_b32 v118, v111 offset:792
	ds_read_b32 v119, v111 offset:924
	s_waitcnt lgkmcnt(0)
	v_cvt_pk_bf16_f32 v120, v112, v113
	v_cvt_pk_bf16_f32 v121, v114, v115
	v_cvt_pk_bf16_f32 v122, v116, v117
	v_cvt_pk_bf16_f32 v123, v118, v119
	s_add_u32 s100, s82, 0x900000
	s_addc_u32 s101, s83, 0
	global_store_dwordx4 v124, v[120:123], s[100:101] sc1
	v_mov_b32_e32 v2, v12
	v_readlane_b32 s2, v253, 0
	v_readlane_b32 s3, v253, 1
	s_mov_b64 s[20:21], exec
	v_readlane_b32 s22, v254, 6
	s_nop 3
	s_mov_b32 exec_lo, s22
	s_mov_b32 exec_hi, 0
	s_cbranch_execz .Lsplit1_join
	v_mov_b32_e32 v240, 0x7000
	v_mov_b32_e32 v242, 0

.LBB0_74:
	v_lshl_add_u64 v[36:37], s[8:9], 0, v[34:35]
	v_lshl_add_u64 v[38:39], s[14:15], 0, v[34:35]
	global_load_dword v44, v[36:37], off
	v_add_co_u32_e32 v36, vcc, 0xb12000, v38
	s_add_u32 s8, s8, s10
	s_nop 0
	v_addc_co_u32_e32 v37, vcc, 0, v39, vcc
	v_add_co_u32_e32 v40, vcc, 0xb15000, v38
	s_addc_u32 s9, s9, s11
	s_nop 0
	v_addc_co_u32_e32 v41, vcc, 0, v39, vcc
	v_add_co_u32_e32 v42, vcc, 0xb18000, v38
	global_load_dword v45, v[36:37], off
	s_nop 0
	global_load_dword v40, v[40:41], off
	v_addc_co_u32_e32 v43, vcc, 0, v39, vcc
	v_add_co_u32_e32 v36, vcc, 0xb1b000, v38
	v_add_u32_e32 v1, s6, v1
	s_nop 0
	v_addc_co_u32_e32 v37, vcc, 0, v39, vcc
	global_load_dword v41, v[42:43], off
	s_nop 0
	global_load_dword v42, v[36:37], off
	s_add_u32 s14, s14, s10
	v_cmp_lt_i32_e32 vcc, s7, v1
	s_addc_u32 s15, s15, s11
	s_or_b64 s[12:13], vcc, s[12:13]
	v_add_co_u32_e32 v36, vcc, 0xb40000, v38
	s_waitcnt vmcnt(3)
	v_add_f32_e32 v38, v44, v45
	s_waitcnt vmcnt(2)
	v_add_f32_e32 v38, v38, v40
	v_addc_co_u32_e32 v37, vcc, 0, v39, vcc
	s_waitcnt vmcnt(1)
	v_add_f32_e32 v38, v38, v41
	s_waitcnt vmcnt(0)
	v_add_f32_e32 v38, v38, v42
	global_store_dword v[36:37], v38, off sc1
	s_andn2_b64 exec, exec, s[12:13]
	s_cbranch_execnz .LBB0_74

.LBB0_83:
	s_waitcnt vmcnt(3) lgkmcnt(7)
	v_pk_mul_f32 v[214:215], v[8:9], v[8:9]
	s_waitcnt lgkmcnt(6)
	v_pk_mul_f32 v[216:217], v[6:7], v[6:7]
	s_waitcnt vmcnt(0)
	v_mul_f32_e32 v213, v10, v10
	s_waitcnt lgkmcnt(5)
	v_pk_mov_b32 v[218:219], v[216:217], v[214:215] op_sel:[1,0]
	v_mov_b32_e32 v217, v215
	v_pk_add_f32 v[214:215], v[218:219], v[216:217]
	v_pk_mul_f32 v[216:217], v[4:5], v[4:5]
	v_pk_mul_f32 v[218:219], v[2:3], v[2:3]
	v_pk_add_f32 v[214:215], v[214:215], v[214:215] op_sel:[0,1] op_sel_hi:[1,0]
	s_waitcnt lgkmcnt(4)
	v_pk_mov_b32 v[220:221], v[218:219], v[216:217] op_sel:[1,0]
	v_mov_b32_e32 v219, v217
	v_pk_add_f32 v[216:217], v[220:221], v[218:219]
	v_mul_f32_e32 v218, v11, v11
	v_pk_add_f32 v[216:217], v[216:217], v[216:217] op_sel:[0,1] op_sel_hi:[1,0]
	v_mov_b32_e32 v215, v213
	v_mov_b32_e32 v217, v218
	v_pk_add_f32 v[214:215], v[214:215], v[216:217]
	v_mul_f32_e32 v216, v15, v15
	v_mul_f32_e32 v219, v12, v12
	v_pk_fma_f32 v[216:217], v[14:15], v[14:15], v[216:217] op_sel_hi:[1,1,0]
	v_mul_f32_e32 v218, v17, v17
	v_mul_f32_e32 v220, v13, v13
	v_mov_b32_e32 v217, v219
	v_pk_fma_f32 v[218:219], v[16:17], v[16:17], v[218:219] op_sel_hi:[1,1,0]
	s_add_i32 s20, s29, s35
	v_mov_b32_e32 v219, v220
	v_pk_add_f32 v[216:217], v[216:217], v[218:219]
	s_ashr_i32 s21, s20, 31
	v_pk_add_f32 v[214:215], v[214:215], v[216:217]
	s_lshl_b64 s[4:5], s[20:21], 11
	v_add_f32_e32 v213, v214, v215
	s_nop 1
	v_add_f32_dpp v213, v213, v213 quad_perm:[1,0,3,2] row_mask:0xf bank_mask:0xf bound_ctrl:1
	s_nop 1
	v_add_f32_dpp v213, v213, v213 quad_perm:[2,3,0,1] row_mask:0xf bank_mask:0xf bound_ctrl:1
	s_nop 1
	v_add_f32_dpp v213, v213, v213 row_half_mirror row_mask:0xf bank_mask:0xf bound_ctrl:1
	s_nop 1
	v_add_f32_dpp v213, v213, v213 row_mirror row_mask:0xf bank_mask:0xf bound_ctrl:1
	ds_bpermute_b32 v214, v200, v213
	s_waitcnt lgkmcnt(0)
	v_add_f32_e32 v213, v213, v214
	ds_bpermute_b32 v214, v203, v213
	s_waitcnt lgkmcnt(0)
	v_add_f32_e32 v213, v213, v214
	v_fmamk_f32 v213, v213, 0x3a800000, v211
	v_rsq_f32_e32 v230, v213
	ds_read_b128 v[214:217], v210
	ds_read_b128 v[218:221], v210 offset:4096
	ds_read_b128 v[222:225], v210 offset:1024
	ds_read_b128 v[226:229], v210 offset:5120
	v_pk_mul_f32 v[6:7], v[6:7], v[230:231] op_sel_hi:[1,0]
	v_pk_mul_f32 v[8:9], v[8:9], v[230:231] op_sel_hi:[1,0]
	s_waitcnt lgkmcnt(2)
	v_pk_fma_f32 v[6:7], v[214:215], v[6:7], v[218:219]
	v_pk_fma_f32 v[8:9], v[216:217], v[8:9], v[220:221]
	ds_read_b128 v[214:217], v210 offset:2048
	ds_read_b128 v[218:221], v210 offset:6144
	v_pk_mul_f32 v[2:3], v[2:3], v[230:231] op_sel_hi:[1,0]
	v_pk_mul_f32 v[4:5], v[4:5], v[230:231] op_sel_hi:[1,0]
	s_waitcnt lgkmcnt(2)
	v_pk_fma_f32 v[2:3], v[222:223], v[2:3], v[226:227]
	v_pk_fma_f32 v[4:5], v[224:225], v[4:5], v[228:229]
	ds_read_b128 v[222:225], v210 offset:3072
	ds_read_b128 v[226:229], v210 offset:7168
	v_pk_mul_f32 v[14:15], v[14:15], v[230:231] op_sel_hi:[1,0]
	v_pk_mul_f32 v[16:17], v[16:17], v[230:231] op_sel_hi:[1,0]
	s_waitcnt lgkmcnt(2)
	v_pk_fma_f32 v[14:15], v[214:215], v[14:15], v[218:219]
	v_pk_fma_f32 v[16:17], v[216:217], v[16:17], v[220:221]
	v_lshl_add_u64 v[214:215], v[206:207], 0, s[4:5]
	v_cvt_pk_bf16_f32 v216, v6, v7
	v_cvt_pk_bf16_f32 v217, v8, v9
	v_pk_mul_f32 v[10:11], v[10:11], v[230:231] op_sel_hi:[1,0]
	v_pk_mul_f32 v[12:13], v[12:13], v[230:231] op_sel_hi:[1,0]
	global_store_dwordx2 v[214:215], v[216:217], off sc1
	v_cvt_pk_bf16_f32 v216, v2, v3
	v_cvt_pk_bf16_f32 v217, v4, v5
	s_waitcnt lgkmcnt(0)
	v_pk_fma_f32 v[12:13], v[224:225], v[12:13], v[228:229]
	v_pk_fma_f32 v[10:11], v[222:223], v[10:11], v[226:227]
	global_store_dwordx2 v[214:215], v[216:217], off offset:512 sc1
	v_cvt_pk_bf16_f32 v216, v14, v15
	v_cvt_pk_bf16_f32 v217, v16, v17
	global_store_dwordx2 v[214:215], v[216:217], off offset:1024 sc1
	v_cvt_pk_bf16_f32 v216, v10, v11
	v_cvt_pk_bf16_f32 v217, v12, v13
	global_store_dwordx2 v[214:215], v[216:217], off offset:1536 sc1
	v_fma_f32 v213, v6, v162, 0
	v_fma_f32 v214, v7, v163, 0
	v_fmac_f32_e32 v213, v8, v164
	v_fmac_f32_e32 v214, v9, v165
	v_fmac_f32_e32 v213, v2, v158
	v_fmac_f32_e32 v214, v3, v159
	v_fmac_f32_e32 v213, v4, v160
	v_fmac_f32_e32 v214, v5, v161
	v_fmac_f32_e32 v213, v14, v154
	v_fmac_f32_e32 v214, v15, v155
	v_fmac_f32_e32 v213, v16, v156
	v_fmac_f32_e32 v214, v17, v157
	v_fmac_f32_e32 v213, v10, v150
	v_fmac_f32_e32 v214, v11, v151
	v_fmac_f32_e32 v213, v12, v152
	v_fmac_f32_e32 v214, v13, v153
	v_add_f32_e32 v213, v214, v213
	v_fma_f32 v214, v6, v146, 0
	v_fma_f32 v215, v7, v147, 0
	v_fmac_f32_e32 v214, v8, v148
	v_fmac_f32_e32 v215, v9, v149
	v_fmac_f32_e32 v214, v2, v142
	v_fmac_f32_e32 v215, v3, v143
	v_fmac_f32_e32 v214, v4, v144
	v_fmac_f32_e32 v215, v5, v145
	v_fmac_f32_e32 v214, v14, v138
	v_fmac_f32_e32 v215, v15, v139
	v_fmac_f32_e32 v214, v16, v140
	v_fmac_f32_e32 v215, v17, v141
	v_fmac_f32_e32 v214, v10, v134
	v_fmac_f32_e32 v215, v11, v135
	v_fmac_f32_e32 v214, v12, v136
	v_fmac_f32_e32 v215, v13, v137
	v_add_f32_e32 v214, v215, v214
	v_fma_f32 v216, v7, v131, 0
	v_fmac_f32_e32 v216, v9, v133
	v_add_f32_dpp v214, v214, v214 quad_perm:[1,0,3,2] row_mask:0xf bank_mask:0xf bound_ctrl:1
	v_fmac_f32_e32 v216, v3, v127
	v_fmac_f32_e32 v216, v5, v129
	v_add_f32_dpp v214, v214, v214 quad_perm:[2,3,0,1] row_mask:0xf bank_mask:0xf bound_ctrl:1
	v_fmac_f32_e32 v216, v15, v123
	v_fmac_f32_e32 v216, v17, v125
	v_add_f32_dpp v214, v214, v214 row_half_mirror row_mask:0xf bank_mask:0xf bound_ctrl:1
	v_fmac_f32_e32 v216, v11, v119
	v_fmac_f32_e32 v216, v13, v121
	v_add_f32_dpp v215, v214, v214 row_mirror row_mask:0xf bank_mask:0xf bound_ctrl:1
	v_fma_f32 v214, v6, v130, 0
	v_fmac_f32_e32 v214, v8, v132
	v_fmac_f32_e32 v214, v2, v126
	v_fmac_f32_e32 v214, v4, v128
	v_fmac_f32_e32 v214, v14, v122
	v_fmac_f32_e32 v214, v16, v124
	v_fmac_f32_e32 v214, v10, v118
	v_fmac_f32_e32 v214, v12, v120
	v_add_f32_e32 v214, v216, v214
	v_fma_f32 v216, v7, v115, 0
	v_fmac_f32_e32 v216, v9, v117
	v_add_f32_dpp v214, v214, v214 quad_perm:[1,0,3,2] row_mask:0xf bank_mask:0xf bound_ctrl:1
	v_fmac_f32_e32 v216, v3, v111
	v_fmac_f32_e32 v216, v5, v113
	v_add_f32_dpp v214, v214, v214 quad_perm:[2,3,0,1] row_mask:0xf bank_mask:0xf bound_ctrl:1
	v_fmac_f32_e32 v216, v15, v107
	v_fmac_f32_e32 v216, v17, v109
	v_add_f32_dpp v214, v214, v214 row_half_mirror row_mask:0xf bank_mask:0xf bound_ctrl:1
	v_fmac_f32_e32 v216, v11, v103
	v_fmac_f32_e32 v216, v13, v105
	v_add_f32_dpp v217, v214, v214 row_mirror row_mask:0xf bank_mask:0xf bound_ctrl:1
	v_fma_f32 v214, v6, v114, 0
	v_fmac_f32_e32 v214, v8, v116
	v_fmac_f32_e32 v214, v2, v110
	v_fmac_f32_e32 v214, v4, v112
	v_fmac_f32_e32 v214, v14, v106
	v_fmac_f32_e32 v214, v16, v108
	v_fmac_f32_e32 v214, v10, v102
	v_fmac_f32_e32 v214, v12, v104
	v_add_f32_e32 v214, v216, v214
	v_fma_f32 v216, v7, v99, 0
	v_fmac_f32_e32 v216, v9, v101
	v_add_f32_dpp v214, v214, v214 quad_perm:[1,0,3,2] row_mask:0xf bank_mask:0xf bound_ctrl:1
	v_fmac_f32_e32 v216, v3, v95
	v_fmac_f32_e32 v216, v5, v97
	v_add_f32_dpp v214, v214, v214 quad_perm:[2,3,0,1] row_mask:0xf bank_mask:0xf bound_ctrl:1
	v_fmac_f32_e32 v216, v15, v91
	v_fmac_f32_e32 v216, v17, v93
	v_add_f32_dpp v214, v214, v214 row_half_mirror row_mask:0xf bank_mask:0xf bound_ctrl:1
	v_fmac_f32_e32 v216, v11, v87
	v_fmac_f32_e32 v216, v13, v89
	v_add_f32_dpp v219, v214, v214 row_mirror row_mask:0xf bank_mask:0xf bound_ctrl:1
	v_fma_f32 v214, v6, v98, 0
	v_fmac_f32_e32 v214, v8, v100
	v_fmac_f32_e32 v214, v2, v94
	v_fmac_f32_e32 v214, v4, v96
	v_fmac_f32_e32 v214, v14, v90
	v_fmac_f32_e32 v214, v16, v92
	v_fmac_f32_e32 v214, v10, v86
	v_fmac_f32_e32 v214, v12, v88
	v_add_f32_e32 v214, v216, v214
	v_fma_f32 v216, v7, v83, 0
	v_fmac_f32_e32 v216, v9, v85
	v_add_f32_dpp v214, v214, v214 quad_perm:[1,0,3,2] row_mask:0xf bank_mask:0xf bound_ctrl:1
	v_fmac_f32_e32 v216, v3, v79
	v_fmac_f32_e32 v216, v5, v81
	v_add_f32_dpp v214, v214, v214 quad_perm:[2,3,0,1] row_mask:0xf bank_mask:0xf bound_ctrl:1
	v_fmac_f32_e32 v216, v15, v75
	v_fmac_f32_e32 v216, v17, v77
	v_add_f32_dpp v214, v214, v214 row_half_mirror row_mask:0xf bank_mask:0xf bound_ctrl:1
	v_fmac_f32_e32 v216, v11, v71
	v_fmac_f32_e32 v216, v13, v73
	v_add_f32_dpp v221, v214, v214 row_mirror row_mask:0xf bank_mask:0xf bound_ctrl:1
	v_fma_f32 v214, v6, v82, 0
	v_fmac_f32_e32 v214, v8, v84
	v_fmac_f32_e32 v214, v2, v78
	v_fmac_f32_e32 v214, v4, v80
	v_fmac_f32_e32 v214, v14, v74
	v_fmac_f32_e32 v214, v16, v76
	v_fmac_f32_e32 v214, v10, v70
	v_fmac_f32_e32 v214, v12, v72
	v_add_f32_e32 v214, v216, v214
	v_fma_f32 v216, v7, v67, 0
	v_fmac_f32_e32 v216, v9, v69
	v_add_f32_dpp v214, v214, v214 quad_perm:[1,0,3,2] row_mask:0xf bank_mask:0xf bound_ctrl:1
	v_fmac_f32_e32 v216, v3, v63
	v_fmac_f32_e32 v216, v5, v65
	v_add_f32_dpp v214, v214, v214 quad_perm:[2,3,0,1] row_mask:0xf bank_mask:0xf bound_ctrl:1
	v_fmac_f32_e32 v216, v15, v59
	v_fmac_f32_e32 v216, v17, v61
	v_add_f32_dpp v214, v214, v214 row_half_mirror row_mask:0xf bank_mask:0xf bound_ctrl:1
	v_fmac_f32_e32 v216, v11, v55
	v_fmac_f32_e32 v216, v13, v57
	v_add_f32_dpp v223, v214, v214 row_mirror row_mask:0xf bank_mask:0xf bound_ctrl:1
	v_fma_f32 v214, v6, v66, 0
	v_fmac_f32_e32 v214, v8, v68
	v_fmac_f32_e32 v214, v2, v62
	v_fmac_f32_e32 v214, v4, v64
	v_fmac_f32_e32 v214, v14, v58
	v_fmac_f32_e32 v214, v16, v60
	v_fmac_f32_e32 v214, v10, v54
	v_fmac_f32_e32 v214, v12, v56
	v_add_f32_e32 v214, v216, v214
	v_fma_f32 v216, v7, v51, 0
	v_fmac_f32_e32 v216, v9, v53
	v_add_f32_dpp v214, v214, v214 quad_perm:[1,0,3,2] row_mask:0xf bank_mask:0xf bound_ctrl:1
	v_fmac_f32_e32 v216, v3, v47
	v_fmac_f32_e32 v216, v5, v49
	v_add_f32_dpp v214, v214, v214 quad_perm:[2,3,0,1] row_mask:0xf bank_mask:0xf bound_ctrl:1
	v_fmac_f32_e32 v216, v15, v43
	v_fmac_f32_e32 v216, v17, v45
	v_add_f32_dpp v214, v214, v214 row_half_mirror row_mask:0xf bank_mask:0xf bound_ctrl:1
	v_fmac_f32_e32 v216, v11, v39
	v_fmac_f32_e32 v216, v13, v41
	v_add_f32_dpp v225, v214, v214 row_mirror row_mask:0xf bank_mask:0xf bound_ctrl:1
	v_fma_f32 v214, v6, v50, 0
	v_fmac_f32_e32 v214, v8, v52
	v_fmac_f32_e32 v214, v2, v46
	v_fmac_f32_e32 v214, v4, v48
	v_fmac_f32_e32 v214, v14, v42
	v_fmac_f32_e32 v214, v16, v44
	v_fmac_f32_e32 v214, v10, v38
	v_fmac_f32_e32 v214, v12, v40
	v_add_f32_e32 v214, v216, v214
	v_add_f32_dpp v213, v213, v213 quad_perm:[1,0,3,2] row_mask:0xf bank_mask:0xf bound_ctrl:1
	ds_bpermute_b32 v218, v200, v215
	v_add_f32_dpp v214, v214, v214 quad_perm:[1,0,3,2] row_mask:0xf bank_mask:0xf bound_ctrl:1
	v_add_f32_dpp v213, v213, v213 quad_perm:[2,3,0,1] row_mask:0xf bank_mask:0xf bound_ctrl:1
	ds_bpermute_b32 v220, v200, v217
	v_add_f32_dpp v214, v214, v214 quad_perm:[2,3,0,1] row_mask:0xf bank_mask:0xf bound_ctrl:1
	v_add_f32_dpp v213, v213, v213 row_half_mirror row_mask:0xf bank_mask:0xf bound_ctrl:1
	ds_bpermute_b32 v222, v200, v219
	v_add_f32_dpp v214, v214, v214 row_half_mirror row_mask:0xf bank_mask:0xf bound_ctrl:1
	v_add_f32_dpp v213, v213, v213 row_mirror row_mask:0xf bank_mask:0xf bound_ctrl:1
	ds_bpermute_b32 v216, v200, v213
	v_add_f32_dpp v227, v214, v214 row_mirror row_mask:0xf bank_mask:0xf bound_ctrl:1
	ds_bpermute_b32 v224, v200, v221
	ds_bpermute_b32 v226, v200, v223
	ds_bpermute_b32 v228, v200, v225
	ds_bpermute_b32 v229, v200, v227
	s_waitcnt lgkmcnt(4)
	v_add_f32_e32 v213, v213, v216
	v_add_f32_e32 v215, v215, v218
	v_add_f32_e32 v217, v217, v220
	v_add_f32_e32 v219, v219, v222
	s_waitcnt lgkmcnt(3)
	v_add_f32_e32 v221, v221, v224
	s_waitcnt lgkmcnt(2)
	v_add_f32_e32 v223, v223, v226
	s_waitcnt lgkmcnt(1)
	v_add_f32_e32 v225, v225, v228
	s_waitcnt lgkmcnt(0)
	v_add_f32_e32 v227, v227, v229
	ds_bpermute_b32 v214, v203, v213
	ds_bpermute_b32 v216, v203, v215
	ds_bpermute_b32 v218, v203, v217
	ds_bpermute_b32 v220, v203, v219
	ds_bpermute_b32 v222, v203, v221
	ds_bpermute_b32 v224, v203, v223
	ds_bpermute_b32 v226, v203, v225
	ds_bpermute_b32 v228, v203, v227
	s_and_saveexec_b64 s[22:23], s[2:3]
	s_cbranch_execz .LBB0_85
	s_waitcnt lgkmcnt(0)
	v_add_f32_e32 v227, v227, v228
	v_add_f32_e32 v225, v225, v226
	s_waitcnt vmcnt(4)
	v_add_f32_e32 v226, v37, v227
	v_mul_f32_e64 v227, |v226|, s30
	v_exp_f32_e32 v227, v227
	v_add_f32_e32 v221, v221, v222
	v_add_f32_e32 v222, v219, v220
	v_add_f32_e32 v213, v213, v214
	v_add_f32_e32 v219, 1.0, v227
	v_cmp_gt_f32_e32 vcc, s31, v219
	v_add_f32_e32 v227, v215, v216
	v_add_f32_e32 v216, v36, v225
	v_cndmask_b32_e64 v220, 0, 32, vcc
	v_ldexp_f32 v219, v219, v220
	v_log_f32_e32 v219, v219
	v_mul_f32_e64 v215, |v216|, s30
	v_exp_f32_e32 v215, v215
	v_add_f32_e32 v223, v223, v224
	v_mul_f32_e32 v214, 0x3f317217, v219
	v_fma_f32 v214, v219, s33, -v214
	v_fmac_f32_e32 v214, 0x3377d1cf, v219
	v_fmac_f32_e32 v214, 0x3f317217, v219
	v_cmp_lt_f32_e64 s[4:5], |v219|, s34
	v_add_f32_e32 v215, 1.0, v215
	v_add_f32_e32 v224, v217, v218
	v_cndmask_b32_e64 v214, v219, v214, s[4:5]
	v_cmp_gt_f32_e64 s[4:5], s31, v215
	v_add_f32_e32 v220, v35, v223
	v_mul_f32_e64 v219, |v220|, s30
	v_cndmask_b32_e64 v217, 0, 32, s[4:5]
	v_ldexp_f32 v215, v215, v217
	v_log_f32_e32 v218, v215
	v_cndmask_b32_e32 v215, 0, v212, vcc
	v_sub_f32_e32 v215, v214, v215
	v_exp_f32_e32 v219, v219
	v_mul_f32_e32 v214, 0x3f317217, v218
	v_fma_f32 v214, v218, s33, -v214
	v_fmac_f32_e32 v214, 0x3377d1cf, v218
	v_fmac_f32_e32 v214, 0x3f317217, v218
	v_cmp_lt_f32_e64 vcc, |v218|, s34
	v_add_f32_e32 v223, v34, v221
	v_mul_f32_e64 v221, |v223|, s30
	v_cndmask_b32_e32 v214, v218, v214, vcc
	v_add_f32_e32 v218, 1.0, v219
	v_cmp_gt_f32_e32 vcc, s31, v218
	v_exp_f32_e32 v221, v221
	v_mul_f32_e32 v213, 0xbfb8aa3b, v213
	v_cndmask_b32_e64 v219, 0, 32, vcc
	v_ldexp_f32 v218, v218, v219
	v_log_f32_e32 v218, v218
	v_cndmask_b32_e64 v219, 0, v212, s[4:5]
	v_sub_f32_e32 v214, v214, v219
	v_exp_f32_e32 v213, v213
	v_mul_f32_e32 v219, 0x3f317217, v218
	v_fma_f32 v219, v218, s33, -v219
	v_fmac_f32_e32 v219, 0x3377d1cf, v218
	v_fmac_f32_e32 v219, 0x3f317217, v218
	v_cmp_lt_f32_e64 s[4:5], |v218|, s34
	v_mul_f32_e32 v222, 0xbfb8aa3b, v222
	v_max_f32_e32 v217, 0, v226
	v_cndmask_b32_e64 v218, v218, v219, s[4:5]
	v_add_f32_e32 v219, 1.0, v221
	v_cmp_gt_f32_e64 s[4:5], s31, v219
	v_max_f32_e32 v216, 0, v216
	v_exp_f32_e32 v222, v222
	v_cndmask_b32_e64 v221, 0, 32, s[4:5]
	v_ldexp_f32 v219, v219, v221
	v_log_f32_e32 v225, v219
	v_cndmask_b32_e32 v219, 0, v212, vcc
	v_sub_f32_e32 v219, v218, v219
	v_max_f32_e32 v221, 0, v220
	v_mul_f32_e32 v218, 0x3f317217, v225
	v_fma_f32 v218, v225, s33, -v218
	v_fmac_f32_e32 v218, 0x3377d1cf, v225
	v_fmac_f32_e32 v218, 0x3f317217, v225
	v_cmp_lt_f32_e64 vcc, |v225|, s34
	v_cndmask_b32_e64 v220, 0, v212, s[4:5]
	v_pk_add_f32 v[214:215], v[216:217], v[214:215]
	v_cndmask_b32_e32 v218, v225, v218, vcc
	v_sub_f32_e32 v218, v218, v220
	v_max_f32_e32 v220, 0, v223
	v_mul_f32_e32 v223, 0xbfb8aa3b, v224
	v_mul_f32_e32 v224, 0xbfb8aa3b, v227
	v_exp_f32_e32 v224, v224
	v_exp_f32_e32 v223, v223
	v_pk_add_f32 v[218:219], v[220:221], v[218:219]
	v_add_f32_e32 v213, 1.0, v213
	v_pk_mul_f32 v[216:217], v[214:215], s[10:11]
	v_pk_mul_f32 v[214:215], v[218:219], s[8:9] neg_lo:[0,1] neg_hi:[0,1]
	v_rcp_f32_e32 v218, v213
	v_add_f32_e32 v213, 1.0, v224
	v_rcp_f32_e32 v219, v213
	v_add_f32_e32 v213, 1.0, v223
	v_rcp_f32_e32 v220, v213
	v_add_f32_e32 v213, 1.0, v222
	s_lshl_b64 s[4:5], s[20:21], 4
	v_rcp_f32_e32 v221, v213
	s_add_u32 s20, s24, s4
	s_addc_u32 s21, s25, s5
	s_add_u32 s4, s26, s4
	s_addc_u32 s5, s27, s5
	global_store_dwordx4 v201, v[218:221], s[20:21] sc1
	global_store_dwordx4 v201, v[214:217], s[4:5] sc1

.LBB0_90:
	s_waitcnt lgkmcnt(7)
	v_pk_mul_f32 v[214:215], v[24:25], v[24:25]
	s_waitcnt lgkmcnt(6)
	v_pk_mul_f32 v[216:217], v[22:23], v[22:23]
	v_mul_f32_e32 v213, v26, v26
	s_waitcnt lgkmcnt(5)
	v_pk_mov_b32 v[218:219], v[216:217], v[214:215] op_sel:[1,0]
	v_mov_b32_e32 v217, v215
	v_pk_add_f32 v[214:215], v[218:219], v[216:217]
	v_pk_mul_f32 v[216:217], v[20:21], v[20:21]
	v_pk_mul_f32 v[218:219], v[18:19], v[18:19]
	v_pk_add_f32 v[214:215], v[214:215], v[214:215] op_sel:[0,1] op_sel_hi:[1,0]
	s_waitcnt lgkmcnt(4)
	v_pk_mov_b32 v[220:221], v[218:219], v[216:217] op_sel:[1,0]
	v_mov_b32_e32 v219, v217
	v_pk_add_f32 v[216:217], v[220:221], v[218:219]
	v_mul_f32_e32 v218, v27, v27
	v_pk_add_f32 v[216:217], v[216:217], v[216:217] op_sel:[0,1] op_sel_hi:[1,0]
	v_mov_b32_e32 v215, v213
	v_mov_b32_e32 v217, v218
	v_pk_add_f32 v[214:215], v[214:215], v[216:217]
	v_mul_f32_e32 v216, v31, v31
	v_mul_f32_e32 v219, v28, v28
	v_pk_fma_f32 v[216:217], v[30:31], v[30:31], v[216:217] op_sel_hi:[1,1,0]
	v_mul_f32_e32 v218, v33, v33
	v_mul_f32_e32 v220, v29, v29
	v_mov_b32_e32 v217, v219
	v_pk_fma_f32 v[218:219], v[32:33], v[32:33], v[218:219] op_sel_hi:[1,1,0]
	s_ashr_i32 s21, s20, 31
	v_mov_b32_e32 v219, v220
	v_pk_add_f32 v[216:217], v[216:217], v[218:219]
	s_lshl_b64 s[4:5], s[20:21], 11
	v_pk_add_f32 v[214:215], v[214:215], v[216:217]
	s_nop 0
	v_add_f32_e32 v213, v214, v215
	s_nop 1
	v_add_f32_dpp v213, v213, v213 quad_perm:[1,0,3,2] row_mask:0xf bank_mask:0xf bound_ctrl:1
	s_nop 1
	v_add_f32_dpp v213, v213, v213 quad_perm:[2,3,0,1] row_mask:0xf bank_mask:0xf bound_ctrl:1
	s_nop 1
	v_add_f32_dpp v213, v213, v213 row_half_mirror row_mask:0xf bank_mask:0xf bound_ctrl:1
	s_nop 1
	v_add_f32_dpp v213, v213, v213 row_mirror row_mask:0xf bank_mask:0xf bound_ctrl:1
	ds_bpermute_b32 v214, v200, v213
	s_waitcnt lgkmcnt(0)
	v_add_f32_e32 v213, v213, v214
	ds_bpermute_b32 v214, v203, v213
	s_waitcnt lgkmcnt(0)
	v_add_f32_e32 v213, v213, v214
	v_fmamk_f32 v213, v213, 0x3a800000, v211
	v_rsq_f32_e32 v230, v213
	ds_read_b128 v[214:217], v210
	ds_read_b128 v[218:221], v210 offset:4096
	ds_read_b128 v[222:225], v210 offset:1024
	ds_read_b128 v[226:229], v210 offset:5120
	v_pk_mul_f32 v[22:23], v[22:23], v[230:231] op_sel_hi:[1,0]
	v_pk_mul_f32 v[24:25], v[24:25], v[230:231] op_sel_hi:[1,0]
	s_waitcnt lgkmcnt(2)
	v_pk_fma_f32 v[22:23], v[214:215], v[22:23], v[218:219]
	v_pk_fma_f32 v[24:25], v[216:217], v[24:25], v[220:221]
	ds_read_b128 v[214:217], v210 offset:2048
	ds_read_b128 v[218:221], v210 offset:6144
	v_pk_mul_f32 v[18:19], v[18:19], v[230:231] op_sel_hi:[1,0]
	v_pk_mul_f32 v[20:21], v[20:21], v[230:231] op_sel_hi:[1,0]
	s_waitcnt lgkmcnt(2)
	v_pk_fma_f32 v[18:19], v[222:223], v[18:19], v[226:227]
	v_pk_fma_f32 v[20:21], v[224:225], v[20:21], v[228:229]
	ds_read_b128 v[222:225], v210 offset:3072
	ds_read_b128 v[226:229], v210 offset:7168
	v_pk_mul_f32 v[30:31], v[30:31], v[230:231] op_sel_hi:[1,0]
	v_pk_mul_f32 v[32:33], v[32:33], v[230:231] op_sel_hi:[1,0]
	s_waitcnt lgkmcnt(2)
	v_pk_fma_f32 v[30:31], v[214:215], v[30:31], v[218:219]
	v_pk_fma_f32 v[32:33], v[216:217], v[32:33], v[220:221]
	v_lshl_add_u64 v[214:215], v[206:207], 0, s[4:5]
	v_cvt_pk_bf16_f32 v216, v22, v23
	v_cvt_pk_bf16_f32 v217, v24, v25
	v_pk_mul_f32 v[26:27], v[26:27], v[230:231] op_sel_hi:[1,0]
	v_pk_mul_f32 v[28:29], v[28:29], v[230:231] op_sel_hi:[1,0]
	global_store_dwordx2 v[214:215], v[216:217], off sc1
	v_cvt_pk_bf16_f32 v216, v18, v19
	v_cvt_pk_bf16_f32 v217, v20, v21
	s_waitcnt lgkmcnt(0)
	v_pk_fma_f32 v[28:29], v[224:225], v[28:29], v[228:229]
	v_pk_fma_f32 v[26:27], v[222:223], v[26:27], v[226:227]
	global_store_dwordx2 v[214:215], v[216:217], off offset:512 sc1
	v_cvt_pk_bf16_f32 v216, v30, v31
	v_cvt_pk_bf16_f32 v217, v32, v33
	global_store_dwordx2 v[214:215], v[216:217], off offset:1024 sc1
	v_cvt_pk_bf16_f32 v216, v26, v27
	v_cvt_pk_bf16_f32 v217, v28, v29
	global_store_dwordx2 v[214:215], v[216:217], off offset:1536 sc1
	v_fma_f32 v213, v22, v162, 0
	v_fma_f32 v214, v23, v163, 0
	v_fmac_f32_e32 v213, v24, v164
	v_fmac_f32_e32 v214, v25, v165
	v_fmac_f32_e32 v213, v18, v158
	v_fmac_f32_e32 v214, v19, v159
	v_fmac_f32_e32 v213, v20, v160
	v_fmac_f32_e32 v214, v21, v161
	v_fmac_f32_e32 v213, v30, v154
	v_fmac_f32_e32 v214, v31, v155
	v_fmac_f32_e32 v213, v32, v156
	v_fmac_f32_e32 v214, v33, v157
	v_fmac_f32_e32 v213, v26, v150
	v_fmac_f32_e32 v214, v27, v151
	v_fmac_f32_e32 v213, v28, v152
	v_fmac_f32_e32 v214, v29, v153
	v_add_f32_e32 v213, v214, v213
	v_fma_f32 v214, v22, v146, 0
	v_fma_f32 v215, v23, v147, 0
	v_fmac_f32_e32 v214, v24, v148
	v_fmac_f32_e32 v215, v25, v149
	v_fmac_f32_e32 v214, v18, v142
	v_fmac_f32_e32 v215, v19, v143
	v_fmac_f32_e32 v214, v20, v144
	v_fmac_f32_e32 v215, v21, v145
	v_fmac_f32_e32 v214, v30, v138
	v_fmac_f32_e32 v215, v31, v139
	v_fmac_f32_e32 v214, v32, v140
	v_fmac_f32_e32 v215, v33, v141
	v_fmac_f32_e32 v214, v26, v134
	v_fmac_f32_e32 v215, v27, v135
	v_fmac_f32_e32 v214, v28, v136
	v_fmac_f32_e32 v215, v29, v137
	v_add_f32_e32 v214, v215, v214
	v_fma_f32 v216, v23, v131, 0
	v_fmac_f32_e32 v216, v25, v133
	v_add_f32_dpp v214, v214, v214 quad_perm:[1,0,3,2] row_mask:0xf bank_mask:0xf bound_ctrl:1
	v_fmac_f32_e32 v216, v19, v127
	v_fmac_f32_e32 v216, v21, v129
	v_add_f32_dpp v214, v214, v214 quad_perm:[2,3,0,1] row_mask:0xf bank_mask:0xf bound_ctrl:1
	v_fmac_f32_e32 v216, v31, v123
	v_fmac_f32_e32 v216, v33, v125
	v_add_f32_dpp v214, v214, v214 row_half_mirror row_mask:0xf bank_mask:0xf bound_ctrl:1
	v_fmac_f32_e32 v216, v27, v119
	v_fmac_f32_e32 v216, v29, v121
	v_add_f32_dpp v215, v214, v214 row_mirror row_mask:0xf bank_mask:0xf bound_ctrl:1
	v_fma_f32 v214, v22, v130, 0
	v_fmac_f32_e32 v214, v24, v132
	v_fmac_f32_e32 v214, v18, v126
	v_fmac_f32_e32 v214, v20, v128
	v_fmac_f32_e32 v214, v30, v122
	v_fmac_f32_e32 v214, v32, v124
	v_fmac_f32_e32 v214, v26, v118
	v_fmac_f32_e32 v214, v28, v120
	v_add_f32_e32 v214, v216, v214
	v_fma_f32 v216, v23, v115, 0
	v_fmac_f32_e32 v216, v25, v117
	v_add_f32_dpp v214, v214, v214 quad_perm:[1,0,3,2] row_mask:0xf bank_mask:0xf bound_ctrl:1
	v_fmac_f32_e32 v216, v19, v111
	v_fmac_f32_e32 v216, v21, v113
	v_add_f32_dpp v214, v214, v214 quad_perm:[2,3,0,1] row_mask:0xf bank_mask:0xf bound_ctrl:1
	v_fmac_f32_e32 v216, v31, v107
	v_fmac_f32_e32 v216, v33, v109
	v_add_f32_dpp v214, v214, v214 row_half_mirror row_mask:0xf bank_mask:0xf bound_ctrl:1
	v_fmac_f32_e32 v216, v27, v103
	v_fmac_f32_e32 v216, v29, v105
	v_add_f32_dpp v217, v214, v214 row_mirror row_mask:0xf bank_mask:0xf bound_ctrl:1
	v_fma_f32 v214, v22, v114, 0
	v_fmac_f32_e32 v214, v24, v116
	v_fmac_f32_e32 v214, v18, v110
	v_fmac_f32_e32 v214, v20, v112
	v_fmac_f32_e32 v214, v30, v106
	v_fmac_f32_e32 v214, v32, v108
	v_fmac_f32_e32 v214, v26, v102
	v_fmac_f32_e32 v214, v28, v104
	v_add_f32_e32 v214, v216, v214
	v_fma_f32 v216, v23, v99, 0
	v_fmac_f32_e32 v216, v25, v101
	v_add_f32_dpp v214, v214, v214 quad_perm:[1,0,3,2] row_mask:0xf bank_mask:0xf bound_ctrl:1
	v_fmac_f32_e32 v216, v19, v95
	v_fmac_f32_e32 v216, v21, v97
	v_add_f32_dpp v214, v214, v214 quad_perm:[2,3,0,1] row_mask:0xf bank_mask:0xf bound_ctrl:1
	v_fmac_f32_e32 v216, v31, v91
	v_fmac_f32_e32 v216, v33, v93
	v_add_f32_dpp v214, v214, v214 row_half_mirror row_mask:0xf bank_mask:0xf bound_ctrl:1
	v_fmac_f32_e32 v216, v27, v87
	v_fmac_f32_e32 v216, v29, v89
	v_add_f32_dpp v219, v214, v214 row_mirror row_mask:0xf bank_mask:0xf bound_ctrl:1
	v_fma_f32 v214, v22, v98, 0
	v_fmac_f32_e32 v214, v24, v100
	v_fmac_f32_e32 v214, v18, v94
	v_fmac_f32_e32 v214, v20, v96
	v_fmac_f32_e32 v214, v30, v90
	v_fmac_f32_e32 v214, v32, v92
	v_fmac_f32_e32 v214, v26, v86
	v_fmac_f32_e32 v214, v28, v88
	v_add_f32_e32 v214, v216, v214
	v_fma_f32 v216, v23, v83, 0
	v_fmac_f32_e32 v216, v25, v85
	v_add_f32_dpp v214, v214, v214 quad_perm:[1,0,3,2] row_mask:0xf bank_mask:0xf bound_ctrl:1
	v_fmac_f32_e32 v216, v19, v79
	v_fmac_f32_e32 v216, v21, v81
	v_add_f32_dpp v214, v214, v214 quad_perm:[2,3,0,1] row_mask:0xf bank_mask:0xf bound_ctrl:1
	v_fmac_f32_e32 v216, v31, v75
	v_fmac_f32_e32 v216, v33, v77
	v_add_f32_dpp v214, v214, v214 row_half_mirror row_mask:0xf bank_mask:0xf bound_ctrl:1
	v_fmac_f32_e32 v216, v27, v71
	v_fmac_f32_e32 v216, v29, v73
	v_add_f32_dpp v221, v214, v214 row_mirror row_mask:0xf bank_mask:0xf bound_ctrl:1
	v_fma_f32 v214, v22, v82, 0
	v_fmac_f32_e32 v214, v24, v84
	v_fmac_f32_e32 v214, v18, v78
	v_fmac_f32_e32 v214, v20, v80
	v_fmac_f32_e32 v214, v30, v74
	v_fmac_f32_e32 v214, v32, v76
	v_fmac_f32_e32 v214, v26, v70
	v_fmac_f32_e32 v214, v28, v72
	v_add_f32_e32 v214, v216, v214
	v_fma_f32 v216, v23, v67, 0
	v_fmac_f32_e32 v216, v25, v69
	v_add_f32_dpp v214, v214, v214 quad_perm:[1,0,3,2] row_mask:0xf bank_mask:0xf bound_ctrl:1
	v_fmac_f32_e32 v216, v19, v63
	v_fmac_f32_e32 v216, v21, v65
	v_add_f32_dpp v214, v214, v214 quad_perm:[2,3,0,1] row_mask:0xf bank_mask:0xf bound_ctrl:1
	v_fmac_f32_e32 v216, v31, v59
	v_fmac_f32_e32 v216, v33, v61
	v_add_f32_dpp v214, v214, v214 row_half_mirror row_mask:0xf bank_mask:0xf bound_ctrl:1
	v_fmac_f32_e32 v216, v27, v55
	v_fmac_f32_e32 v216, v29, v57
	v_add_f32_dpp v223, v214, v214 row_mirror row_mask:0xf bank_mask:0xf bound_ctrl:1
	v_fma_f32 v214, v22, v66, 0
	v_fmac_f32_e32 v214, v24, v68
	v_fmac_f32_e32 v214, v18, v62
	v_fmac_f32_e32 v214, v20, v64
	v_fmac_f32_e32 v214, v30, v58
	v_fmac_f32_e32 v214, v32, v60
	v_fmac_f32_e32 v214, v26, v54
	v_fmac_f32_e32 v214, v28, v56
	v_add_f32_e32 v214, v216, v214
	v_fma_f32 v216, v23, v51, 0
	v_fmac_f32_e32 v216, v25, v53
	v_add_f32_dpp v214, v214, v214 quad_perm:[1,0,3,2] row_mask:0xf bank_mask:0xf bound_ctrl:1
	v_fmac_f32_e32 v216, v19, v47
	v_fmac_f32_e32 v216, v21, v49
	v_add_f32_dpp v214, v214, v214 quad_perm:[2,3,0,1] row_mask:0xf bank_mask:0xf bound_ctrl:1
	v_fmac_f32_e32 v216, v31, v43
	v_fmac_f32_e32 v216, v33, v45
	v_add_f32_dpp v214, v214, v214 row_half_mirror row_mask:0xf bank_mask:0xf bound_ctrl:1
	v_fmac_f32_e32 v216, v27, v39
	v_fmac_f32_e32 v216, v29, v41
	v_add_f32_dpp v225, v214, v214 row_mirror row_mask:0xf bank_mask:0xf bound_ctrl:1
	v_fma_f32 v214, v22, v50, 0
	v_fmac_f32_e32 v214, v24, v52
	v_fmac_f32_e32 v214, v18, v46
	v_fmac_f32_e32 v214, v20, v48
	v_fmac_f32_e32 v214, v30, v42
	v_fmac_f32_e32 v214, v32, v44
	v_fmac_f32_e32 v214, v26, v38
	v_fmac_f32_e32 v214, v28, v40
	v_add_f32_e32 v214, v216, v214
	v_add_f32_dpp v213, v213, v213 quad_perm:[1,0,3,2] row_mask:0xf bank_mask:0xf bound_ctrl:1
	ds_bpermute_b32 v218, v200, v215
	v_add_f32_dpp v214, v214, v214 quad_perm:[1,0,3,2] row_mask:0xf bank_mask:0xf bound_ctrl:1
	v_add_f32_dpp v213, v213, v213 quad_perm:[2,3,0,1] row_mask:0xf bank_mask:0xf bound_ctrl:1
	ds_bpermute_b32 v220, v200, v217
	v_add_f32_dpp v214, v214, v214 quad_perm:[2,3,0,1] row_mask:0xf bank_mask:0xf bound_ctrl:1
	v_add_f32_dpp v213, v213, v213 row_half_mirror row_mask:0xf bank_mask:0xf bound_ctrl:1
	ds_bpermute_b32 v222, v200, v219
	v_add_f32_dpp v214, v214, v214 row_half_mirror row_mask:0xf bank_mask:0xf bound_ctrl:1
	v_add_f32_dpp v213, v213, v213 row_mirror row_mask:0xf bank_mask:0xf bound_ctrl:1
	ds_bpermute_b32 v216, v200, v213
	v_add_f32_dpp v227, v214, v214 row_mirror row_mask:0xf bank_mask:0xf bound_ctrl:1
	ds_bpermute_b32 v224, v200, v221
	ds_bpermute_b32 v226, v200, v223
	ds_bpermute_b32 v228, v200, v225
	ds_bpermute_b32 v229, v200, v227
	s_waitcnt lgkmcnt(4)
	v_add_f32_e32 v213, v213, v216
	v_add_f32_e32 v215, v215, v218
	v_add_f32_e32 v217, v217, v220
	v_add_f32_e32 v219, v219, v222
	s_waitcnt lgkmcnt(3)
	v_add_f32_e32 v221, v221, v224
	s_waitcnt lgkmcnt(2)
	v_add_f32_e32 v223, v223, v226
	s_waitcnt lgkmcnt(1)
	v_add_f32_e32 v225, v225, v228
	s_waitcnt lgkmcnt(0)
	v_add_f32_e32 v227, v227, v229
	ds_bpermute_b32 v214, v203, v213
	ds_bpermute_b32 v216, v203, v215
	ds_bpermute_b32 v218, v203, v217
	ds_bpermute_b32 v220, v203, v219
	ds_bpermute_b32 v222, v203, v221
	ds_bpermute_b32 v224, v203, v223
	ds_bpermute_b32 v226, v203, v225
	ds_bpermute_b32 v228, v203, v227
	s_and_saveexec_b64 s[22:23], s[2:3]
	s_cbranch_execz .LBB0_92
	s_waitcnt lgkmcnt(0)
	v_add_f32_e32 v227, v227, v228
	v_add_f32_e32 v225, v225, v226
	s_waitcnt vmcnt(8)
	v_add_f32_e32 v226, v37, v227
	v_mul_f32_e64 v227, |v226|, s30
	v_exp_f32_e32 v227, v227
	v_add_f32_e32 v221, v221, v222
	v_add_f32_e32 v222, v219, v220
	v_add_f32_e32 v213, v213, v214
	v_add_f32_e32 v219, 1.0, v227
	v_cmp_gt_f32_e32 vcc, s31, v219
	v_add_f32_e32 v227, v215, v216
	v_add_f32_e32 v216, v36, v225
	v_cndmask_b32_e64 v220, 0, 32, vcc
	v_ldexp_f32 v219, v219, v220
	v_log_f32_e32 v219, v219
	v_mul_f32_e64 v215, |v216|, s30
	v_exp_f32_e32 v215, v215
	v_add_f32_e32 v223, v223, v224
	v_mul_f32_e32 v214, 0x3f317217, v219
	v_fma_f32 v214, v219, s33, -v214
	v_fmac_f32_e32 v214, 0x3377d1cf, v219
	v_fmac_f32_e32 v214, 0x3f317217, v219
	v_cmp_lt_f32_e64 s[4:5], |v219|, s34
	v_add_f32_e32 v215, 1.0, v215
	v_add_f32_e32 v224, v217, v218
	v_cndmask_b32_e64 v214, v219, v214, s[4:5]
	v_cmp_gt_f32_e64 s[4:5], s31, v215
	v_add_f32_e32 v220, v35, v223
	v_mul_f32_e64 v219, |v220|, s30
	v_cndmask_b32_e64 v217, 0, 32, s[4:5]
	v_ldexp_f32 v215, v215, v217
	v_log_f32_e32 v218, v215
	v_cndmask_b32_e32 v215, 0, v212, vcc
	v_sub_f32_e32 v215, v214, v215
	v_exp_f32_e32 v219, v219
	v_mul_f32_e32 v214, 0x3f317217, v218
	v_fma_f32 v214, v218, s33, -v214
	v_fmac_f32_e32 v214, 0x3377d1cf, v218
	v_fmac_f32_e32 v214, 0x3f317217, v218
	v_cmp_lt_f32_e64 vcc, |v218|, s34
	v_add_f32_e32 v223, v34, v221
	v_mul_f32_e64 v221, |v223|, s30
	v_cndmask_b32_e32 v214, v218, v214, vcc
	v_add_f32_e32 v218, 1.0, v219
	v_cmp_gt_f32_e32 vcc, s31, v218
	v_exp_f32_e32 v221, v221
	v_mul_f32_e32 v213, 0xbfb8aa3b, v213
	v_cndmask_b32_e64 v219, 0, 32, vcc
	v_ldexp_f32 v218, v218, v219
	v_log_f32_e32 v218, v218
	v_cndmask_b32_e64 v219, 0, v212, s[4:5]
	v_sub_f32_e32 v214, v214, v219
	v_exp_f32_e32 v213, v213
	v_mul_f32_e32 v219, 0x3f317217, v218
	v_fma_f32 v219, v218, s33, -v219
	v_fmac_f32_e32 v219, 0x3377d1cf, v218
	v_fmac_f32_e32 v219, 0x3f317217, v218
	v_cmp_lt_f32_e64 s[4:5], |v218|, s34
	v_mul_f32_e32 v222, 0xbfb8aa3b, v222
	v_max_f32_e32 v217, 0, v226
	v_cndmask_b32_e64 v218, v218, v219, s[4:5]
	v_add_f32_e32 v219, 1.0, v221
	v_cmp_gt_f32_e64 s[4:5], s31, v219
	v_max_f32_e32 v216, 0, v216
	v_exp_f32_e32 v222, v222
	v_cndmask_b32_e64 v221, 0, 32, s[4:5]
	v_ldexp_f32 v219, v219, v221
	v_log_f32_e32 v225, v219
	v_cndmask_b32_e32 v219, 0, v212, vcc
	v_sub_f32_e32 v219, v218, v219
	v_max_f32_e32 v221, 0, v220
	v_mul_f32_e32 v218, 0x3f317217, v225
	v_fma_f32 v218, v225, s33, -v218
	v_fmac_f32_e32 v218, 0x3377d1cf, v225
	v_fmac_f32_e32 v218, 0x3f317217, v225
	v_cmp_lt_f32_e64 vcc, |v225|, s34
	v_cndmask_b32_e64 v220, 0, v212, s[4:5]
	v_pk_add_f32 v[214:215], v[216:217], v[214:215]
	v_cndmask_b32_e32 v218, v225, v218, vcc
	v_sub_f32_e32 v218, v218, v220
	v_max_f32_e32 v220, 0, v223
	v_mul_f32_e32 v223, 0xbfb8aa3b, v224
	v_mul_f32_e32 v224, 0xbfb8aa3b, v227
	v_exp_f32_e32 v224, v224
	v_exp_f32_e32 v223, v223
	v_pk_add_f32 v[218:219], v[220:221], v[218:219]
	v_add_f32_e32 v213, 1.0, v213
	v_pk_mul_f32 v[216:217], v[214:215], s[10:11]
	v_pk_mul_f32 v[214:215], v[218:219], s[8:9] neg_lo:[0,1] neg_hi:[0,1]
	v_rcp_f32_e32 v218, v213
	v_add_f32_e32 v213, 1.0, v224
	v_rcp_f32_e32 v219, v213
	v_add_f32_e32 v213, 1.0, v223
	v_rcp_f32_e32 v220, v213
	v_add_f32_e32 v213, 1.0, v222
	s_lshl_b64 s[4:5], s[20:21], 4
	v_rcp_f32_e32 v221, v213
	s_add_u32 s20, s24, s4
	s_addc_u32 s21, s25, s5
	s_add_u32 s4, s26, s4
	s_addc_u32 s5, s27, s5
	global_store_dwordx4 v201, v[218:221], s[20:21] sc1
	global_store_dwordx4 v201, v[214:217], s[4:5] sc1

.LBB0_95:
	s_waitcnt vmcnt(7) lgkmcnt(7)
	v_pk_mul_f32 v[214:215], v[172:173], v[172:173]
	s_waitcnt lgkmcnt(6)
	v_pk_mul_f32 v[216:217], v[170:171], v[170:171]
	s_waitcnt vmcnt(4)
	v_mul_f32_e32 v213, v178, v178
	s_waitcnt lgkmcnt(5)
	v_pk_mov_b32 v[218:219], v[216:217], v[214:215] op_sel:[1,0]
	v_mov_b32_e32 v217, v215
	v_pk_add_f32 v[214:215], v[218:219], v[216:217]
	v_pk_mul_f32 v[216:217], v[168:169], v[168:169]
	v_pk_mul_f32 v[218:219], v[166:167], v[166:167]
	v_pk_add_f32 v[214:215], v[214:215], v[214:215] op_sel:[0,1] op_sel_hi:[1,0]
	s_waitcnt lgkmcnt(4)
	v_pk_mov_b32 v[220:221], v[218:219], v[216:217] op_sel:[1,0]
	v_mov_b32_e32 v219, v217
	v_pk_add_f32 v[216:217], v[220:221], v[218:219]
	v_mul_f32_e32 v218, v179, v179
	v_pk_add_f32 v[216:217], v[216:217], v[216:217] op_sel:[0,1] op_sel_hi:[1,0]
	v_mov_b32_e32 v215, v213
	v_mov_b32_e32 v217, v218
	v_pk_add_f32 v[214:215], v[214:215], v[216:217]
	v_mul_f32_e32 v216, v187, v187
	v_mul_f32_e32 v219, v180, v180
	v_pk_fma_f32 v[216:217], v[186:187], v[186:187], v[216:217] op_sel_hi:[1,1,0]
	v_mul_f32_e32 v218, v189, v189
	v_mul_f32_e32 v220, v181, v181
	v_mov_b32_e32 v217, v219
	v_pk_fma_f32 v[218:219], v[188:189], v[188:189], v[218:219] op_sel_hi:[1,1,0]
	s_ashr_i32 s17, s16, 31
	v_mov_b32_e32 v219, v220
	v_pk_add_f32 v[216:217], v[216:217], v[218:219]
	s_lshl_b64 s[4:5], s[16:17], 11
	v_pk_add_f32 v[214:215], v[214:215], v[216:217]
	s_nop 0
	v_add_f32_e32 v213, v214, v215
	s_nop 1
	v_add_f32_dpp v213, v213, v213 quad_perm:[1,0,3,2] row_mask:0xf bank_mask:0xf bound_ctrl:1
	s_nop 1
	v_add_f32_dpp v213, v213, v213 quad_perm:[2,3,0,1] row_mask:0xf bank_mask:0xf bound_ctrl:1
	s_nop 1
	v_add_f32_dpp v213, v213, v213 row_half_mirror row_mask:0xf bank_mask:0xf bound_ctrl:1
	s_nop 1
	v_add_f32_dpp v213, v213, v213 row_mirror row_mask:0xf bank_mask:0xf bound_ctrl:1
	ds_bpermute_b32 v214, v200, v213
	s_waitcnt lgkmcnt(0)
	v_add_f32_e32 v213, v213, v214
	ds_bpermute_b32 v214, v203, v213
	s_waitcnt lgkmcnt(0)
	v_add_f32_e32 v213, v213, v214
	v_fmamk_f32 v213, v213, 0x3a800000, v211
	v_rsq_f32_e32 v230, v213
	ds_read_b128 v[214:217], v210
	ds_read_b128 v[218:221], v210 offset:4096
	ds_read_b128 v[222:225], v210 offset:1024
	ds_read_b128 v[226:229], v210 offset:5120
	v_pk_mul_f32 v[170:171], v[170:171], v[230:231] op_sel_hi:[1,0]
	v_pk_mul_f32 v[172:173], v[172:173], v[230:231] op_sel_hi:[1,0]
	s_waitcnt lgkmcnt(2)
	v_pk_fma_f32 v[170:171], v[214:215], v[170:171], v[218:219]
	v_pk_fma_f32 v[172:173], v[216:217], v[172:173], v[220:221]
	ds_read_b128 v[214:217], v210 offset:2048
	ds_read_b128 v[218:221], v210 offset:6144
	v_pk_mul_f32 v[166:167], v[166:167], v[230:231] op_sel_hi:[1,0]
	v_pk_mul_f32 v[168:169], v[168:169], v[230:231] op_sel_hi:[1,0]
	s_waitcnt lgkmcnt(2)
	v_pk_fma_f32 v[166:167], v[222:223], v[166:167], v[226:227]
	v_pk_fma_f32 v[168:169], v[224:225], v[168:169], v[228:229]
	ds_read_b128 v[222:225], v210 offset:3072
	ds_read_b128 v[226:229], v210 offset:7168
	v_pk_mul_f32 v[186:187], v[186:187], v[230:231] op_sel_hi:[1,0]
	v_pk_mul_f32 v[188:189], v[188:189], v[230:231] op_sel_hi:[1,0]
	s_waitcnt lgkmcnt(2)
	v_pk_fma_f32 v[186:187], v[214:215], v[186:187], v[218:219]
	v_pk_fma_f32 v[188:189], v[216:217], v[188:189], v[220:221]
	v_lshl_add_u64 v[214:215], v[206:207], 0, s[4:5]
	v_cvt_pk_bf16_f32 v216, v170, v171
	v_cvt_pk_bf16_f32 v217, v172, v173
	v_pk_mul_f32 v[178:179], v[178:179], v[230:231] op_sel_hi:[1,0]
	v_pk_mul_f32 v[180:181], v[180:181], v[230:231] op_sel_hi:[1,0]
	global_store_dwordx2 v[214:215], v[216:217], off sc1
	v_cvt_pk_bf16_f32 v216, v166, v167
	v_cvt_pk_bf16_f32 v217, v168, v169
	s_waitcnt lgkmcnt(0)
	v_pk_fma_f32 v[180:181], v[224:225], v[180:181], v[228:229]
	v_pk_fma_f32 v[178:179], v[222:223], v[178:179], v[226:227]
	global_store_dwordx2 v[214:215], v[216:217], off offset:512 sc1
	v_cvt_pk_bf16_f32 v216, v186, v187
	v_cvt_pk_bf16_f32 v217, v188, v189
	global_store_dwordx2 v[214:215], v[216:217], off offset:1024 sc1
	v_cvt_pk_bf16_f32 v216, v178, v179
	v_cvt_pk_bf16_f32 v217, v180, v181
	global_store_dwordx2 v[214:215], v[216:217], off offset:1536 sc1
	v_fma_f32 v213, v170, v162, 0
	v_fma_f32 v214, v171, v163, 0
	v_fmac_f32_e32 v213, v172, v164
	v_fmac_f32_e32 v214, v173, v165
	v_fmac_f32_e32 v213, v166, v158
	v_fmac_f32_e32 v214, v167, v159
	v_fmac_f32_e32 v213, v168, v160
	v_fmac_f32_e32 v214, v169, v161
	v_fmac_f32_e32 v213, v186, v154
	v_fmac_f32_e32 v214, v187, v155
	v_fmac_f32_e32 v213, v188, v156
	v_fmac_f32_e32 v214, v189, v157
	v_fmac_f32_e32 v213, v178, v150
	v_fmac_f32_e32 v214, v179, v151
	v_fmac_f32_e32 v213, v180, v152
	v_fmac_f32_e32 v214, v181, v153
	v_add_f32_e32 v213, v213, v214
	v_fma_f32 v214, v170, v146, 0
	v_fma_f32 v215, v171, v147, 0
	v_fmac_f32_e32 v214, v172, v148
	v_fmac_f32_e32 v215, v173, v149
	v_fmac_f32_e32 v214, v166, v142
	v_fmac_f32_e32 v215, v167, v143
	v_fmac_f32_e32 v214, v168, v144
	v_fmac_f32_e32 v215, v169, v145
	v_fmac_f32_e32 v214, v186, v138
	v_fmac_f32_e32 v215, v187, v139
	v_fmac_f32_e32 v214, v188, v140
	v_fmac_f32_e32 v215, v189, v141
	v_fmac_f32_e32 v214, v178, v134
	v_fmac_f32_e32 v215, v179, v135
	v_fmac_f32_e32 v214, v180, v136
	v_fmac_f32_e32 v215, v181, v137
	v_add_f32_e32 v214, v214, v215
	v_fma_f32 v216, v171, v131, 0
	v_fmac_f32_e32 v216, v173, v133
	v_add_f32_dpp v214, v214, v214 quad_perm:[1,0,3,2] row_mask:0xf bank_mask:0xf bound_ctrl:1
	v_fmac_f32_e32 v216, v167, v127
	v_fmac_f32_e32 v216, v169, v129
	v_add_f32_dpp v214, v214, v214 quad_perm:[2,3,0,1] row_mask:0xf bank_mask:0xf bound_ctrl:1
	v_fmac_f32_e32 v216, v187, v123
	v_fmac_f32_e32 v216, v189, v125
	v_add_f32_dpp v214, v214, v214 row_half_mirror row_mask:0xf bank_mask:0xf bound_ctrl:1
	v_fmac_f32_e32 v216, v179, v119
	v_fmac_f32_e32 v216, v181, v121
	v_add_f32_dpp v215, v214, v214 row_mirror row_mask:0xf bank_mask:0xf bound_ctrl:1
	v_fma_f32 v214, v170, v130, 0
	v_fmac_f32_e32 v214, v172, v132
	v_fmac_f32_e32 v214, v166, v126
	v_fmac_f32_e32 v214, v168, v128
	v_fmac_f32_e32 v214, v186, v122
	v_fmac_f32_e32 v214, v188, v124
	v_fmac_f32_e32 v214, v178, v118
	v_fmac_f32_e32 v214, v180, v120
	v_add_f32_e32 v214, v214, v216
	v_fma_f32 v216, v171, v115, 0
	v_fmac_f32_e32 v216, v173, v117
	v_add_f32_dpp v214, v214, v214 quad_perm:[1,0,3,2] row_mask:0xf bank_mask:0xf bound_ctrl:1
	v_fmac_f32_e32 v216, v167, v111
	v_fmac_f32_e32 v216, v169, v113
	v_add_f32_dpp v214, v214, v214 quad_perm:[2,3,0,1] row_mask:0xf bank_mask:0xf bound_ctrl:1
	v_fmac_f32_e32 v216, v187, v107
	v_fmac_f32_e32 v216, v189, v109
	v_add_f32_dpp v214, v214, v214 row_half_mirror row_mask:0xf bank_mask:0xf bound_ctrl:1
	v_fmac_f32_e32 v216, v179, v103
	v_fmac_f32_e32 v216, v181, v105
	v_add_f32_dpp v217, v214, v214 row_mirror row_mask:0xf bank_mask:0xf bound_ctrl:1
	v_fma_f32 v214, v170, v114, 0
	v_fmac_f32_e32 v214, v172, v116
	v_fmac_f32_e32 v214, v166, v110
	v_fmac_f32_e32 v214, v168, v112
	v_fmac_f32_e32 v214, v186, v106
	v_fmac_f32_e32 v214, v188, v108
	v_fmac_f32_e32 v214, v178, v102
	v_fmac_f32_e32 v214, v180, v104
	v_add_f32_e32 v214, v214, v216
	v_fma_f32 v216, v171, v99, 0
	v_fmac_f32_e32 v216, v173, v101
	v_add_f32_dpp v214, v214, v214 quad_perm:[1,0,3,2] row_mask:0xf bank_mask:0xf bound_ctrl:1
	v_fmac_f32_e32 v216, v167, v95
	v_fmac_f32_e32 v216, v169, v97
	v_add_f32_dpp v214, v214, v214 quad_perm:[2,3,0,1] row_mask:0xf bank_mask:0xf bound_ctrl:1
	v_fmac_f32_e32 v216, v187, v91
	v_fmac_f32_e32 v216, v189, v93
	v_add_f32_dpp v214, v214, v214 row_half_mirror row_mask:0xf bank_mask:0xf bound_ctrl:1
	v_fmac_f32_e32 v216, v179, v87
	v_fmac_f32_e32 v216, v181, v89
	v_add_f32_dpp v219, v214, v214 row_mirror row_mask:0xf bank_mask:0xf bound_ctrl:1
	v_fma_f32 v214, v170, v98, 0
	v_fmac_f32_e32 v214, v172, v100
	v_fmac_f32_e32 v214, v166, v94
	v_fmac_f32_e32 v214, v168, v96
	v_fmac_f32_e32 v214, v186, v90
	v_fmac_f32_e32 v214, v188, v92
	v_fmac_f32_e32 v214, v178, v86
	v_fmac_f32_e32 v214, v180, v88
	v_add_f32_e32 v214, v214, v216
	v_fma_f32 v216, v171, v83, 0
	v_fmac_f32_e32 v216, v173, v85
	v_add_f32_dpp v214, v214, v214 quad_perm:[1,0,3,2] row_mask:0xf bank_mask:0xf bound_ctrl:1
	v_fmac_f32_e32 v216, v167, v79
	v_fmac_f32_e32 v216, v169, v81
	v_add_f32_dpp v214, v214, v214 quad_perm:[2,3,0,1] row_mask:0xf bank_mask:0xf bound_ctrl:1
	v_fmac_f32_e32 v216, v187, v75
	v_fmac_f32_e32 v216, v189, v77
	v_add_f32_dpp v214, v214, v214 row_half_mirror row_mask:0xf bank_mask:0xf bound_ctrl:1
	v_fmac_f32_e32 v216, v179, v71
	v_fmac_f32_e32 v216, v181, v73
	v_add_f32_dpp v221, v214, v214 row_mirror row_mask:0xf bank_mask:0xf bound_ctrl:1
	v_fma_f32 v214, v170, v82, 0
	v_fmac_f32_e32 v214, v172, v84
	v_fmac_f32_e32 v214, v166, v78
	v_fmac_f32_e32 v214, v168, v80
	v_fmac_f32_e32 v214, v186, v74
	v_fmac_f32_e32 v214, v188, v76
	v_fmac_f32_e32 v214, v178, v70
	v_fmac_f32_e32 v214, v180, v72
	v_add_f32_e32 v214, v214, v216
	v_fma_f32 v216, v171, v67, 0
	v_fmac_f32_e32 v216, v173, v69
	v_add_f32_dpp v214, v214, v214 quad_perm:[1,0,3,2] row_mask:0xf bank_mask:0xf bound_ctrl:1
	v_fmac_f32_e32 v216, v167, v63
	v_fmac_f32_e32 v216, v169, v65
	v_add_f32_dpp v214, v214, v214 quad_perm:[2,3,0,1] row_mask:0xf bank_mask:0xf bound_ctrl:1
	v_fmac_f32_e32 v216, v187, v59
	v_fmac_f32_e32 v216, v189, v61
	v_add_f32_dpp v214, v214, v214 row_half_mirror row_mask:0xf bank_mask:0xf bound_ctrl:1
	v_fmac_f32_e32 v216, v179, v55
	v_fmac_f32_e32 v216, v181, v57
	v_add_f32_dpp v223, v214, v214 row_mirror row_mask:0xf bank_mask:0xf bound_ctrl:1
	v_fma_f32 v214, v170, v66, 0
	v_fmac_f32_e32 v214, v172, v68
	v_fmac_f32_e32 v214, v166, v62
	v_fmac_f32_e32 v214, v168, v64
	v_fmac_f32_e32 v214, v186, v58
	v_fmac_f32_e32 v214, v188, v60
	v_fmac_f32_e32 v214, v178, v54
	v_fmac_f32_e32 v214, v180, v56
	v_add_f32_e32 v214, v214, v216
	v_fma_f32 v216, v171, v51, 0
	v_fmac_f32_e32 v216, v173, v53
	v_add_f32_dpp v214, v214, v214 quad_perm:[1,0,3,2] row_mask:0xf bank_mask:0xf bound_ctrl:1
	v_fmac_f32_e32 v216, v167, v47
	v_fmac_f32_e32 v216, v169, v49
	v_add_f32_dpp v214, v214, v214 quad_perm:[2,3,0,1] row_mask:0xf bank_mask:0xf bound_ctrl:1
	v_fmac_f32_e32 v216, v187, v43
	v_fmac_f32_e32 v216, v189, v45
	v_add_f32_dpp v214, v214, v214 row_half_mirror row_mask:0xf bank_mask:0xf bound_ctrl:1
	v_fmac_f32_e32 v216, v179, v39
	v_fmac_f32_e32 v216, v181, v41
	v_add_f32_dpp v225, v214, v214 row_mirror row_mask:0xf bank_mask:0xf bound_ctrl:1
	v_fma_f32 v214, v170, v50, 0
	v_fmac_f32_e32 v214, v172, v52
	v_fmac_f32_e32 v214, v166, v46
	v_fmac_f32_e32 v214, v168, v48
	v_fmac_f32_e32 v214, v186, v42
	v_fmac_f32_e32 v214, v188, v44
	v_fmac_f32_e32 v214, v178, v38
	v_fmac_f32_e32 v214, v180, v40
	v_add_f32_e32 v214, v214, v216
	v_add_f32_dpp v213, v213, v213 quad_perm:[1,0,3,2] row_mask:0xf bank_mask:0xf bound_ctrl:1
	ds_bpermute_b32 v218, v200, v215
	v_add_f32_dpp v214, v214, v214 quad_perm:[1,0,3,2] row_mask:0xf bank_mask:0xf bound_ctrl:1
	v_add_f32_dpp v213, v213, v213 quad_perm:[2,3,0,1] row_mask:0xf bank_mask:0xf bound_ctrl:1
	ds_bpermute_b32 v220, v200, v217
	v_add_f32_dpp v214, v214, v214 quad_perm:[2,3,0,1] row_mask:0xf bank_mask:0xf bound_ctrl:1
	v_add_f32_dpp v213, v213, v213 row_half_mirror row_mask:0xf bank_mask:0xf bound_ctrl:1
	ds_bpermute_b32 v222, v200, v219
	v_add_f32_dpp v214, v214, v214 row_half_mirror row_mask:0xf bank_mask:0xf bound_ctrl:1
	v_add_f32_dpp v213, v213, v213 row_mirror row_mask:0xf bank_mask:0xf bound_ctrl:1
	ds_bpermute_b32 v216, v200, v213
	v_add_f32_dpp v227, v214, v214 row_mirror row_mask:0xf bank_mask:0xf bound_ctrl:1
	ds_bpermute_b32 v224, v200, v221
	ds_bpermute_b32 v226, v200, v223
	ds_bpermute_b32 v228, v200, v225
	ds_bpermute_b32 v229, v200, v227
	s_waitcnt lgkmcnt(4)
	v_add_f32_e32 v213, v213, v216
	v_add_f32_e32 v215, v215, v218
	v_add_f32_e32 v217, v217, v220
	v_add_f32_e32 v219, v219, v222
	s_waitcnt lgkmcnt(3)
	v_add_f32_e32 v221, v221, v224
	s_waitcnt lgkmcnt(2)
	v_add_f32_e32 v223, v223, v226
	s_waitcnt lgkmcnt(1)
	v_add_f32_e32 v225, v225, v228
	s_waitcnt lgkmcnt(0)
	v_add_f32_e32 v227, v227, v229
	ds_bpermute_b32 v214, v203, v213
	ds_bpermute_b32 v216, v203, v215
	ds_bpermute_b32 v218, v203, v217
	ds_bpermute_b32 v220, v203, v219
	ds_bpermute_b32 v222, v203, v221
	ds_bpermute_b32 v224, v203, v223
	ds_bpermute_b32 v226, v203, v225
	ds_bpermute_b32 v228, v203, v227
	s_and_saveexec_b64 s[18:19], s[2:3]
	s_cbranch_execz .LBB0_97
	s_waitcnt lgkmcnt(0)
	v_add_f32_e32 v227, v227, v228
	v_add_f32_e32 v225, v225, v226
	v_add_f32_e32 v226, v37, v227
	v_mul_f32_e64 v227, |v226|, s30
	v_exp_f32_e32 v227, v227
	v_add_f32_e32 v221, v221, v222
	v_add_f32_e32 v222, v219, v220
	v_add_f32_e32 v213, v213, v214
	v_add_f32_e32 v219, 1.0, v227
	v_cmp_gt_f32_e32 vcc, s31, v219
	v_add_f32_e32 v227, v215, v216
	v_add_f32_e32 v216, v36, v225
	v_cndmask_b32_e64 v220, 0, 32, vcc
	v_ldexp_f32 v219, v219, v220
	v_log_f32_e32 v219, v219
	v_mul_f32_e64 v215, |v216|, s30
	v_exp_f32_e32 v215, v215
	v_add_f32_e32 v223, v223, v224
	v_mul_f32_e32 v214, 0x3f317217, v219
	v_fma_f32 v214, v219, s33, -v214
	v_fmac_f32_e32 v214, 0x3377d1cf, v219
	v_fmac_f32_e32 v214, 0x3f317217, v219
	v_cmp_lt_f32_e64 s[4:5], |v219|, s34
	v_add_f32_e32 v215, 1.0, v215
	v_add_f32_e32 v224, v217, v218
	v_cndmask_b32_e64 v214, v219, v214, s[4:5]
	v_cmp_gt_f32_e64 s[4:5], s31, v215
	v_add_f32_e32 v220, v35, v223
	v_mul_f32_e64 v219, |v220|, s30
	v_cndmask_b32_e64 v217, 0, 32, s[4:5]
	v_ldexp_f32 v215, v215, v217
	v_log_f32_e32 v218, v215
	v_cndmask_b32_e32 v215, 0, v212, vcc
	v_sub_f32_e32 v215, v214, v215
	v_exp_f32_e32 v219, v219
	v_mul_f32_e32 v214, 0x3f317217, v218
	v_fma_f32 v214, v218, s33, -v214
	v_fmac_f32_e32 v214, 0x3377d1cf, v218
	v_fmac_f32_e32 v214, 0x3f317217, v218
	v_cmp_lt_f32_e64 vcc, |v218|, s34
	v_add_f32_e32 v223, v34, v221
	v_mul_f32_e64 v221, |v223|, s30
	v_cndmask_b32_e32 v214, v218, v214, vcc
	v_add_f32_e32 v218, 1.0, v219
	v_cmp_gt_f32_e32 vcc, s31, v218
	v_exp_f32_e32 v221, v221
	v_mul_f32_e32 v213, 0xbfb8aa3b, v213
	v_cndmask_b32_e64 v219, 0, 32, vcc
	v_ldexp_f32 v218, v218, v219
	v_log_f32_e32 v218, v218
	v_cndmask_b32_e64 v219, 0, v212, s[4:5]
	v_sub_f32_e32 v214, v214, v219
	v_exp_f32_e32 v213, v213
	v_mul_f32_e32 v219, 0x3f317217, v218
	v_fma_f32 v219, v218, s33, -v219
	v_fmac_f32_e32 v219, 0x3377d1cf, v218
	v_fmac_f32_e32 v219, 0x3f317217, v218
	v_cmp_lt_f32_e64 s[4:5], |v218|, s34
	v_mul_f32_e32 v222, 0xbfb8aa3b, v222
	v_max_f32_e32 v217, 0, v226
	v_cndmask_b32_e64 v218, v218, v219, s[4:5]
	v_add_f32_e32 v219, 1.0, v221
	v_cmp_gt_f32_e64 s[4:5], s31, v219
	v_max_f32_e32 v216, 0, v216
	v_exp_f32_e32 v222, v222
	v_cndmask_b32_e64 v221, 0, 32, s[4:5]
	v_ldexp_f32 v219, v219, v221
	v_log_f32_e32 v225, v219
	v_cndmask_b32_e32 v219, 0, v212, vcc
	v_sub_f32_e32 v219, v218, v219
	v_max_f32_e32 v221, 0, v220
	v_mul_f32_e32 v218, 0x3f317217, v225
	v_fma_f32 v218, v225, s33, -v218
	v_fmac_f32_e32 v218, 0x3377d1cf, v225
	v_fmac_f32_e32 v218, 0x3f317217, v225
	v_cmp_lt_f32_e64 vcc, |v225|, s34
	v_cndmask_b32_e64 v220, 0, v212, s[4:5]
	v_pk_add_f32 v[214:215], v[216:217], v[214:215]
	v_cndmask_b32_e32 v218, v225, v218, vcc
	v_sub_f32_e32 v218, v218, v220
	v_max_f32_e32 v220, 0, v223
	v_mul_f32_e32 v223, 0xbfb8aa3b, v224
	v_mul_f32_e32 v224, 0xbfb8aa3b, v227
	v_exp_f32_e32 v224, v224
	v_exp_f32_e32 v223, v223
	v_pk_add_f32 v[218:219], v[220:221], v[218:219]
	v_add_f32_e32 v213, 1.0, v213
	v_pk_mul_f32 v[216:217], v[214:215], s[10:11]
	v_pk_mul_f32 v[214:215], v[218:219], s[8:9] neg_lo:[0,1] neg_hi:[0,1]
	v_rcp_f32_e32 v218, v213
	v_add_f32_e32 v213, 1.0, v224
	v_rcp_f32_e32 v219, v213
	v_add_f32_e32 v213, 1.0, v223
	v_rcp_f32_e32 v220, v213
	v_add_f32_e32 v213, 1.0, v222
	s_lshl_b64 s[4:5], s[16:17], 4
	v_rcp_f32_e32 v221, v213
	s_add_u32 s16, s24, s4
	s_addc_u32 s17, s25, s5
	s_add_u32 s4, s26, s4
	s_addc_u32 s5, s27, s5
	global_store_dwordx4 v201, v[218:221], s[16:17] sc1
	global_store_dwordx4 v201, v[214:217], s[4:5] sc1

.LBB0_98:
	s_waitcnt vmcnt(7) lgkmcnt(7)
	v_pk_mul_f32 v[214:215], v[184:185], v[184:185]
	s_waitcnt lgkmcnt(6)
	v_pk_mul_f32 v[216:217], v[182:183], v[182:183]
	s_waitcnt vmcnt(4)
	v_mul_f32_e32 v213, v190, v190
	s_waitcnt lgkmcnt(5)
	v_pk_mov_b32 v[218:219], v[216:217], v[214:215] op_sel:[1,0]
	v_mov_b32_e32 v217, v215
	v_pk_add_f32 v[214:215], v[218:219], v[216:217]
	v_pk_mul_f32 v[216:217], v[176:177], v[176:177]
	v_pk_mul_f32 v[218:219], v[174:175], v[174:175]
	v_pk_add_f32 v[214:215], v[214:215], v[214:215] op_sel:[0,1] op_sel_hi:[1,0]
	s_waitcnt lgkmcnt(4)
	v_pk_mov_b32 v[220:221], v[218:219], v[216:217] op_sel:[1,0]
	v_mov_b32_e32 v219, v217
	v_pk_add_f32 v[216:217], v[220:221], v[218:219]
	v_mul_f32_e32 v218, v191, v191
	v_pk_add_f32 v[216:217], v[216:217], v[216:217] op_sel:[0,1] op_sel_hi:[1,0]
	v_mov_b32_e32 v215, v213
	v_mov_b32_e32 v217, v218
	v_pk_add_f32 v[214:215], v[214:215], v[216:217]
	v_mul_f32_e32 v216, v195, v195
	v_mul_f32_e32 v219, v192, v192
	v_pk_fma_f32 v[216:217], v[194:195], v[194:195], v[216:217] op_sel_hi:[1,1,0]
	v_mul_f32_e32 v218, v197, v197
	v_mul_f32_e32 v220, v193, v193
	v_mov_b32_e32 v217, v219
	v_pk_fma_f32 v[218:219], v[196:197], v[196:197], v[218:219] op_sel_hi:[1,1,0]
	s_ashr_i32 s13, s12, 31
	v_mov_b32_e32 v219, v220
	v_pk_add_f32 v[216:217], v[216:217], v[218:219]
	s_lshl_b64 s[4:5], s[12:13], 11
	v_pk_add_f32 v[214:215], v[214:215], v[216:217]
	s_nop 0
	v_add_f32_e32 v213, v214, v215
	s_nop 1
	v_add_f32_dpp v213, v213, v213 quad_perm:[1,0,3,2] row_mask:0xf bank_mask:0xf bound_ctrl:1
	s_nop 1
	v_add_f32_dpp v213, v213, v213 quad_perm:[2,3,0,1] row_mask:0xf bank_mask:0xf bound_ctrl:1
	s_nop 1
	v_add_f32_dpp v213, v213, v213 row_half_mirror row_mask:0xf bank_mask:0xf bound_ctrl:1
	s_nop 1
	v_add_f32_dpp v213, v213, v213 row_mirror row_mask:0xf bank_mask:0xf bound_ctrl:1
	ds_bpermute_b32 v214, v200, v213
	s_waitcnt lgkmcnt(0)
	v_add_f32_e32 v213, v213, v214
	ds_bpermute_b32 v214, v203, v213
	s_waitcnt lgkmcnt(0)
	v_add_f32_e32 v213, v213, v214
	v_fmamk_f32 v213, v213, 0x3a800000, v211
	v_rsq_f32_e32 v230, v213
	ds_read_b128 v[214:217], v210
	ds_read_b128 v[218:221], v210 offset:4096
	ds_read_b128 v[222:225], v210 offset:1024
	ds_read_b128 v[226:229], v210 offset:5120
	v_pk_mul_f32 v[182:183], v[182:183], v[230:231] op_sel_hi:[1,0]
	v_pk_mul_f32 v[184:185], v[184:185], v[230:231] op_sel_hi:[1,0]
	s_waitcnt lgkmcnt(2)
	v_pk_fma_f32 v[182:183], v[214:215], v[182:183], v[218:219]
	v_pk_fma_f32 v[184:185], v[216:217], v[184:185], v[220:221]
	ds_read_b128 v[214:217], v210 offset:2048
	ds_read_b128 v[218:221], v210 offset:6144
	v_pk_mul_f32 v[174:175], v[174:175], v[230:231] op_sel_hi:[1,0]
	v_pk_mul_f32 v[176:177], v[176:177], v[230:231] op_sel_hi:[1,0]
	s_waitcnt lgkmcnt(2)
	v_pk_fma_f32 v[174:175], v[222:223], v[174:175], v[226:227]
	v_pk_fma_f32 v[176:177], v[224:225], v[176:177], v[228:229]
	ds_read_b128 v[222:225], v210 offset:3072
	ds_read_b128 v[226:229], v210 offset:7168
	v_pk_mul_f32 v[194:195], v[194:195], v[230:231] op_sel_hi:[1,0]
	v_pk_mul_f32 v[196:197], v[196:197], v[230:231] op_sel_hi:[1,0]
	s_waitcnt lgkmcnt(2)
	v_pk_fma_f32 v[194:195], v[214:215], v[194:195], v[218:219]
	v_pk_fma_f32 v[196:197], v[216:217], v[196:197], v[220:221]
	v_lshl_add_u64 v[214:215], v[206:207], 0, s[4:5]
	v_cvt_pk_bf16_f32 v216, v182, v183
	v_cvt_pk_bf16_f32 v217, v184, v185
	v_pk_mul_f32 v[190:191], v[190:191], v[230:231] op_sel_hi:[1,0]
	v_pk_mul_f32 v[192:193], v[192:193], v[230:231] op_sel_hi:[1,0]
	global_store_dwordx2 v[214:215], v[216:217], off sc1
	v_cvt_pk_bf16_f32 v216, v174, v175
	v_cvt_pk_bf16_f32 v217, v176, v177
	s_waitcnt lgkmcnt(0)
	v_pk_fma_f32 v[192:193], v[224:225], v[192:193], v[228:229]
	v_pk_fma_f32 v[190:191], v[222:223], v[190:191], v[226:227]
	global_store_dwordx2 v[214:215], v[216:217], off offset:512 sc1
	v_cvt_pk_bf16_f32 v216, v194, v195
	v_cvt_pk_bf16_f32 v217, v196, v197
	global_store_dwordx2 v[214:215], v[216:217], off offset:1024 sc1
	v_cvt_pk_bf16_f32 v216, v190, v191
	v_cvt_pk_bf16_f32 v217, v192, v193
	global_store_dwordx2 v[214:215], v[216:217], off offset:1536 sc1
	v_fma_f32 v213, v182, v162, 0
	v_fma_f32 v214, v183, v163, 0
	v_fmac_f32_e32 v213, v184, v164
	v_fmac_f32_e32 v214, v185, v165
	v_fmac_f32_e32 v213, v174, v158
	v_fmac_f32_e32 v214, v175, v159
	v_fmac_f32_e32 v213, v176, v160
	v_fmac_f32_e32 v214, v177, v161
	v_fmac_f32_e32 v213, v194, v154
	v_fmac_f32_e32 v214, v195, v155
	v_fmac_f32_e32 v213, v196, v156
	v_fmac_f32_e32 v214, v197, v157
	v_fmac_f32_e32 v213, v190, v150
	v_fmac_f32_e32 v214, v191, v151
	v_fmac_f32_e32 v213, v192, v152
	v_fmac_f32_e32 v214, v193, v153
	v_add_f32_e32 v213, v213, v214
	v_fma_f32 v214, v182, v146, 0
	v_fma_f32 v215, v183, v147, 0
	v_fmac_f32_e32 v214, v184, v148
	v_fmac_f32_e32 v215, v185, v149
	v_fmac_f32_e32 v214, v174, v142
	v_fmac_f32_e32 v215, v175, v143
	v_fmac_f32_e32 v214, v176, v144
	v_fmac_f32_e32 v215, v177, v145
	v_fmac_f32_e32 v214, v194, v138
	v_fmac_f32_e32 v215, v195, v139
	v_fmac_f32_e32 v214, v196, v140
	v_fmac_f32_e32 v215, v197, v141
	v_fmac_f32_e32 v214, v190, v134
	v_fmac_f32_e32 v215, v191, v135
	v_fmac_f32_e32 v214, v192, v136
	v_fmac_f32_e32 v215, v193, v137
	v_add_f32_e32 v214, v214, v215
	v_fma_f32 v216, v183, v131, 0
	v_fmac_f32_e32 v216, v185, v133
	v_add_f32_dpp v214, v214, v214 quad_perm:[1,0,3,2] row_mask:0xf bank_mask:0xf bound_ctrl:1
	v_fmac_f32_e32 v216, v175, v127
	v_fmac_f32_e32 v216, v177, v129
	v_add_f32_dpp v214, v214, v214 quad_perm:[2,3,0,1] row_mask:0xf bank_mask:0xf bound_ctrl:1
	v_fmac_f32_e32 v216, v195, v123
	v_fmac_f32_e32 v216, v197, v125
	v_add_f32_dpp v214, v214, v214 row_half_mirror row_mask:0xf bank_mask:0xf bound_ctrl:1
	v_fmac_f32_e32 v216, v191, v119
	v_fmac_f32_e32 v216, v193, v121
	v_add_f32_dpp v215, v214, v214 row_mirror row_mask:0xf bank_mask:0xf bound_ctrl:1
	v_fma_f32 v214, v182, v130, 0
	v_fmac_f32_e32 v214, v184, v132
	v_fmac_f32_e32 v214, v174, v126
	v_fmac_f32_e32 v214, v176, v128
	v_fmac_f32_e32 v214, v194, v122
	v_fmac_f32_e32 v214, v196, v124
	v_fmac_f32_e32 v214, v190, v118
	v_fmac_f32_e32 v214, v192, v120
	v_add_f32_e32 v214, v214, v216
	v_fma_f32 v216, v183, v115, 0
	v_fmac_f32_e32 v216, v185, v117
	v_add_f32_dpp v214, v214, v214 quad_perm:[1,0,3,2] row_mask:0xf bank_mask:0xf bound_ctrl:1
	v_fmac_f32_e32 v216, v175, v111
	v_fmac_f32_e32 v216, v177, v113
	v_add_f32_dpp v214, v214, v214 quad_perm:[2,3,0,1] row_mask:0xf bank_mask:0xf bound_ctrl:1
	v_fmac_f32_e32 v216, v195, v107
	v_fmac_f32_e32 v216, v197, v109
	v_add_f32_dpp v214, v214, v214 row_half_mirror row_mask:0xf bank_mask:0xf bound_ctrl:1
	v_fmac_f32_e32 v216, v191, v103
	v_fmac_f32_e32 v216, v193, v105
	v_add_f32_dpp v217, v214, v214 row_mirror row_mask:0xf bank_mask:0xf bound_ctrl:1
	v_fma_f32 v214, v182, v114, 0
	v_fmac_f32_e32 v214, v184, v116
	v_fmac_f32_e32 v214, v174, v110
	v_fmac_f32_e32 v214, v176, v112
	v_fmac_f32_e32 v214, v194, v106
	v_fmac_f32_e32 v214, v196, v108
	v_fmac_f32_e32 v214, v190, v102
	v_fmac_f32_e32 v214, v192, v104
	v_add_f32_e32 v214, v214, v216
	v_fma_f32 v216, v183, v99, 0
	v_fmac_f32_e32 v216, v185, v101
	v_add_f32_dpp v214, v214, v214 quad_perm:[1,0,3,2] row_mask:0xf bank_mask:0xf bound_ctrl:1
	v_fmac_f32_e32 v216, v175, v95
	v_fmac_f32_e32 v216, v177, v97
	v_add_f32_dpp v214, v214, v214 quad_perm:[2,3,0,1] row_mask:0xf bank_mask:0xf bound_ctrl:1
	v_fmac_f32_e32 v216, v195, v91
	v_fmac_f32_e32 v216, v197, v93
	v_add_f32_dpp v214, v214, v214 row_half_mirror row_mask:0xf bank_mask:0xf bound_ctrl:1
	v_fmac_f32_e32 v216, v191, v87
	v_fmac_f32_e32 v216, v193, v89
	v_add_f32_dpp v219, v214, v214 row_mirror row_mask:0xf bank_mask:0xf bound_ctrl:1
	v_fma_f32 v214, v182, v98, 0
	v_fmac_f32_e32 v214, v184, v100
	v_fmac_f32_e32 v214, v174, v94
	v_fmac_f32_e32 v214, v176, v96
	v_fmac_f32_e32 v214, v194, v90
	v_fmac_f32_e32 v214, v196, v92
	v_fmac_f32_e32 v214, v190, v86
	v_fmac_f32_e32 v214, v192, v88
	v_add_f32_e32 v214, v214, v216
	v_fma_f32 v216, v183, v83, 0
	v_fmac_f32_e32 v216, v185, v85
	v_add_f32_dpp v214, v214, v214 quad_perm:[1,0,3,2] row_mask:0xf bank_mask:0xf bound_ctrl:1
	v_fmac_f32_e32 v216, v175, v79
	v_fmac_f32_e32 v216, v177, v81
	v_add_f32_dpp v214, v214, v214 quad_perm:[2,3,0,1] row_mask:0xf bank_mask:0xf bound_ctrl:1
	v_fmac_f32_e32 v216, v195, v75
	v_fmac_f32_e32 v216, v197, v77
	v_add_f32_dpp v214, v214, v214 row_half_mirror row_mask:0xf bank_mask:0xf bound_ctrl:1
	v_fmac_f32_e32 v216, v191, v71
	v_fmac_f32_e32 v216, v193, v73
	v_add_f32_dpp v221, v214, v214 row_mirror row_mask:0xf bank_mask:0xf bound_ctrl:1
	v_fma_f32 v214, v182, v82, 0
	v_fmac_f32_e32 v214, v184, v84
	v_fmac_f32_e32 v214, v174, v78
	v_fmac_f32_e32 v214, v176, v80
	v_fmac_f32_e32 v214, v194, v74
	v_fmac_f32_e32 v214, v196, v76
	v_fmac_f32_e32 v214, v190, v70
	v_fmac_f32_e32 v214, v192, v72
	v_add_f32_e32 v214, v214, v216
	v_fma_f32 v216, v183, v67, 0
	v_fmac_f32_e32 v216, v185, v69
	v_add_f32_dpp v214, v214, v214 quad_perm:[1,0,3,2] row_mask:0xf bank_mask:0xf bound_ctrl:1
	v_fmac_f32_e32 v216, v175, v63
	v_fmac_f32_e32 v216, v177, v65
	v_add_f32_dpp v214, v214, v214 quad_perm:[2,3,0,1] row_mask:0xf bank_mask:0xf bound_ctrl:1
	v_fmac_f32_e32 v216, v195, v59
	v_fmac_f32_e32 v216, v197, v61
	v_add_f32_dpp v214, v214, v214 row_half_mirror row_mask:0xf bank_mask:0xf bound_ctrl:1
	v_fmac_f32_e32 v216, v191, v55
	v_fmac_f32_e32 v216, v193, v57
	v_add_f32_dpp v223, v214, v214 row_mirror row_mask:0xf bank_mask:0xf bound_ctrl:1
	v_fma_f32 v214, v182, v66, 0
	v_fmac_f32_e32 v214, v184, v68
	v_fmac_f32_e32 v214, v174, v62
	v_fmac_f32_e32 v214, v176, v64
	v_fmac_f32_e32 v214, v194, v58
	v_fmac_f32_e32 v214, v196, v60
	v_fmac_f32_e32 v214, v190, v54
	v_fmac_f32_e32 v214, v192, v56
	v_add_f32_e32 v214, v214, v216
	v_fma_f32 v216, v183, v51, 0
	v_fmac_f32_e32 v216, v185, v53
	v_add_f32_dpp v214, v214, v214 quad_perm:[1,0,3,2] row_mask:0xf bank_mask:0xf bound_ctrl:1
	v_fmac_f32_e32 v216, v175, v47
	v_fmac_f32_e32 v216, v177, v49
	v_add_f32_dpp v214, v214, v214 quad_perm:[2,3,0,1] row_mask:0xf bank_mask:0xf bound_ctrl:1
	v_fmac_f32_e32 v216, v195, v43
	v_fmac_f32_e32 v216, v197, v45
	v_add_f32_dpp v214, v214, v214 row_half_mirror row_mask:0xf bank_mask:0xf bound_ctrl:1
	v_fmac_f32_e32 v216, v191, v39
	v_fmac_f32_e32 v216, v193, v41
	v_add_f32_dpp v225, v214, v214 row_mirror row_mask:0xf bank_mask:0xf bound_ctrl:1
	v_fma_f32 v214, v182, v50, 0
	v_fmac_f32_e32 v214, v184, v52
	v_fmac_f32_e32 v214, v174, v46
	v_fmac_f32_e32 v214, v176, v48
	v_fmac_f32_e32 v214, v194, v42
	v_fmac_f32_e32 v214, v196, v44
	v_fmac_f32_e32 v214, v190, v38
	v_fmac_f32_e32 v214, v192, v40
	v_add_f32_e32 v214, v214, v216
	v_add_f32_dpp v213, v213, v213 quad_perm:[1,0,3,2] row_mask:0xf bank_mask:0xf bound_ctrl:1
	ds_bpermute_b32 v218, v200, v215
	v_add_f32_dpp v214, v214, v214 quad_perm:[1,0,3,2] row_mask:0xf bank_mask:0xf bound_ctrl:1
	v_add_f32_dpp v213, v213, v213 quad_perm:[2,3,0,1] row_mask:0xf bank_mask:0xf bound_ctrl:1
	ds_bpermute_b32 v220, v200, v217
	v_add_f32_dpp v214, v214, v214 quad_perm:[2,3,0,1] row_mask:0xf bank_mask:0xf bound_ctrl:1
	v_add_f32_dpp v213, v213, v213 row_half_mirror row_mask:0xf bank_mask:0xf bound_ctrl:1
	ds_bpermute_b32 v222, v200, v219
	v_add_f32_dpp v214, v214, v214 row_half_mirror row_mask:0xf bank_mask:0xf bound_ctrl:1
	v_add_f32_dpp v213, v213, v213 row_mirror row_mask:0xf bank_mask:0xf bound_ctrl:1
	ds_bpermute_b32 v216, v200, v213
	v_add_f32_dpp v227, v214, v214 row_mirror row_mask:0xf bank_mask:0xf bound_ctrl:1
	ds_bpermute_b32 v224, v200, v221
	ds_bpermute_b32 v226, v200, v223
	ds_bpermute_b32 v228, v200, v225
	ds_bpermute_b32 v229, v200, v227
	s_waitcnt lgkmcnt(4)
	v_add_f32_e32 v213, v213, v216
	v_add_f32_e32 v215, v215, v218
	v_add_f32_e32 v217, v217, v220
	v_add_f32_e32 v219, v219, v222
	s_waitcnt lgkmcnt(3)
	v_add_f32_e32 v221, v221, v224
	s_waitcnt lgkmcnt(2)
	v_add_f32_e32 v223, v223, v226
	s_waitcnt lgkmcnt(1)
	v_add_f32_e32 v225, v225, v228
	s_waitcnt lgkmcnt(0)
	v_add_f32_e32 v227, v227, v229
	ds_bpermute_b32 v214, v203, v213
	ds_bpermute_b32 v216, v203, v215
	ds_bpermute_b32 v218, v203, v217
	ds_bpermute_b32 v220, v203, v219
	ds_bpermute_b32 v222, v203, v221
	ds_bpermute_b32 v224, v203, v223
	ds_bpermute_b32 v226, v203, v225
	ds_bpermute_b32 v228, v203, v227
	s_and_saveexec_b64 s[14:15], s[2:3]
	s_cbranch_execz .LBB0_77
	s_waitcnt lgkmcnt(0)
	v_add_f32_e32 v227, v227, v228
	v_add_f32_e32 v225, v225, v226
	v_add_f32_e32 v226, v37, v227
	v_mul_f32_e64 v227, |v226|, s30
	v_exp_f32_e32 v227, v227
	v_add_f32_e32 v221, v221, v222
	v_add_f32_e32 v222, v219, v220
	v_add_f32_e32 v213, v213, v214
	v_add_f32_e32 v219, 1.0, v227
	v_cmp_gt_f32_e32 vcc, s31, v219
	v_add_f32_e32 v227, v215, v216
	v_add_f32_e32 v216, v36, v225
	v_cndmask_b32_e64 v220, 0, 32, vcc
	v_ldexp_f32 v219, v219, v220
	v_log_f32_e32 v219, v219
	v_mul_f32_e64 v215, |v216|, s30
	v_exp_f32_e32 v215, v215
	v_add_f32_e32 v223, v223, v224
	v_mul_f32_e32 v214, 0x3f317217, v219
	v_fma_f32 v214, v219, s33, -v214
	v_fmac_f32_e32 v214, 0x3377d1cf, v219
	v_fmac_f32_e32 v214, 0x3f317217, v219
	v_cmp_lt_f32_e64 s[4:5], |v219|, s34
	v_add_f32_e32 v215, 1.0, v215
	v_add_f32_e32 v224, v217, v218
	v_cndmask_b32_e64 v214, v219, v214, s[4:5]
	v_cmp_gt_f32_e64 s[4:5], s31, v215
	v_add_f32_e32 v220, v35, v223
	v_mul_f32_e64 v219, |v220|, s30
	v_cndmask_b32_e64 v217, 0, 32, s[4:5]
	v_ldexp_f32 v215, v215, v217
	v_log_f32_e32 v218, v215
	v_cndmask_b32_e32 v215, 0, v212, vcc
	v_sub_f32_e32 v215, v214, v215
	v_exp_f32_e32 v219, v219
	v_mul_f32_e32 v214, 0x3f317217, v218
	v_fma_f32 v214, v218, s33, -v214
	v_fmac_f32_e32 v214, 0x3377d1cf, v218
	v_fmac_f32_e32 v214, 0x3f317217, v218
	v_cmp_lt_f32_e64 vcc, |v218|, s34
	v_add_f32_e32 v223, v34, v221
	v_mul_f32_e64 v221, |v223|, s30
	v_cndmask_b32_e32 v214, v218, v214, vcc
	v_add_f32_e32 v218, 1.0, v219
	v_cmp_gt_f32_e32 vcc, s31, v218
	v_exp_f32_e32 v221, v221
	v_mul_f32_e32 v213, 0xbfb8aa3b, v213
	v_cndmask_b32_e64 v219, 0, 32, vcc
	v_ldexp_f32 v218, v218, v219
	v_log_f32_e32 v218, v218
	v_cndmask_b32_e64 v219, 0, v212, s[4:5]
	v_sub_f32_e32 v214, v214, v219
	v_exp_f32_e32 v213, v213
	v_mul_f32_e32 v219, 0x3f317217, v218
	v_fma_f32 v219, v218, s33, -v219
	v_fmac_f32_e32 v219, 0x3377d1cf, v218
	v_fmac_f32_e32 v219, 0x3f317217, v218
	v_cmp_lt_f32_e64 s[4:5], |v218|, s34
	v_mul_f32_e32 v222, 0xbfb8aa3b, v222
	v_max_f32_e32 v217, 0, v226
	v_cndmask_b32_e64 v218, v218, v219, s[4:5]
	v_add_f32_e32 v219, 1.0, v221
	v_cmp_gt_f32_e64 s[4:5], s31, v219
	v_max_f32_e32 v216, 0, v216
	v_exp_f32_e32 v222, v222
	v_cndmask_b32_e64 v221, 0, 32, s[4:5]
	v_ldexp_f32 v219, v219, v221
	v_log_f32_e32 v225, v219
	v_cndmask_b32_e32 v219, 0, v212, vcc
	v_sub_f32_e32 v219, v218, v219
	v_max_f32_e32 v221, 0, v220
	v_mul_f32_e32 v218, 0x3f317217, v225
	v_fma_f32 v218, v225, s33, -v218
	v_fmac_f32_e32 v218, 0x3377d1cf, v225
	v_fmac_f32_e32 v218, 0x3f317217, v225
	v_cmp_lt_f32_e64 vcc, |v225|, s34
	v_cndmask_b32_e64 v220, 0, v212, s[4:5]
	v_pk_add_f32 v[214:215], v[216:217], v[214:215]
	v_cndmask_b32_e32 v218, v225, v218, vcc
	v_sub_f32_e32 v218, v218, v220
	v_max_f32_e32 v220, 0, v223
	v_mul_f32_e32 v223, 0xbfb8aa3b, v224
	v_mul_f32_e32 v224, 0xbfb8aa3b, v227
	v_exp_f32_e32 v224, v224
	v_exp_f32_e32 v223, v223
	v_pk_add_f32 v[218:219], v[220:221], v[218:219]
	v_add_f32_e32 v213, 1.0, v213
	v_pk_mul_f32 v[216:217], v[214:215], s[10:11]
	v_pk_mul_f32 v[214:215], v[218:219], s[8:9] neg_lo:[0,1] neg_hi:[0,1]
	v_rcp_f32_e32 v218, v213
	v_add_f32_e32 v213, 1.0, v224
	v_rcp_f32_e32 v219, v213
	v_add_f32_e32 v213, 1.0, v223
	v_rcp_f32_e32 v220, v213
	v_add_f32_e32 v213, 1.0, v222
	s_lshl_b64 s[4:5], s[12:13], 4
	v_rcp_f32_e32 v221, v213
	s_add_u32 s12, s24, s4
	s_addc_u32 s13, s25, s5
	s_add_u32 s4, s26, s4
	s_addc_u32 s5, s27, s5
	global_store_dwordx4 v201, v[218:221], s[12:13] sc1
	global_store_dwordx4 v201, v[214:217], s[4:5] sc1
	s_branch .LBB0_77

.LBB0_151:
	s_andn2_saveexec_b64 s[4:5], s[4:5]
	s_cbranch_execz .LBB0_171
	s_mov_b64 s[4:5], exec
	buffer_inv sc1
	s_waitcnt lgkmcnt(0)
	s_waitcnt vmcnt(0)
	v_mbcnt_lo_u32_b32 v3, s4, 0
	v_mbcnt_hi_u32_b32 v3, s5, v3
	v_cmp_eq_u32_e32 vcc, 0, v3
	s_and_saveexec_b64 s[6:7], vcc
	s_cbranch_execz .LBB0_154
	s_bcnt1_i32_b64 s4, s[4:5]
	v_mov_b32_e32 v4, 0x7000
	v_mov_b32_e32 v5, s4
	global_atomic_add v4, v4, v5, s[82:83] offset:1024 sc0
